# phase3 gate epilogue: per-channel -8*log1p(exp(-lambda)) computed once per tile instead of per element
# speedup vs baseline: 1.0509x; 1.0168x over previous
; DEVI char* wsp(const Params& P, size_t off) { asm volatile("" : "+s"(off)); return P.ws + off; }
; template <int GATE>
; DEVI void gemm_core_t(f32x4 (&acc)[4][4], const bfu* __restrict__ A, int lda,
;                     const bfu* __restrict__ B, int ldb, int K, char* smem, int tid, const bfu* __restrict__ B2 = nullptr) {
;   const int wid = tid >> 6, lane = tid & 63;
;   const int wr = wid >> 1, wc = wid & 1, fr = lane & 15, fq = lane >> 4;
;   const int nt = K >> 6;
;   __syncthreads();
;   stage_tile(A, lda, 0, smem, tid);
;   if (GATE) stage_tile_gate(B, B2, 0, smem + 16384, tid); else stage_tile(B, ldb, 0, smem + 16384, tid);
;   for (int t = 0; t < nt; ++t) {
;     asm volatile("s_waitcnt vmcnt(0)" ::: "memory");
;     __syncthreads();
;     char* cur = smem + (t & 1) * 32768;
;     if (t + 1 < nt) {
;       char* nx = smem + ((t + 1) & 1) * 32768;
;       stage_tile(A, lda, (t + 1) * 64, nx, tid);
;       if (GATE) stage_tile_gate(B, B2, (t + 1) * 64, nx + 16384, tid); else stage_tile(B, ldb, (t + 1) * 64, nx + 16384, tid);
;     }
; #pragma unroll
;     for (int kk = 0; kk < 2; ++kk) {
;       bf16x8 af[4], bfr[4];
; #pragma unroll
;       for (int m = 0; m < 4; ++m) af[m] = ldfrag(cur, wr * 64 + m * 16 + fr, kk * 4 + fq);
; #pragma unroll
;       for (int n = 0; n < 4; ++n) bfr[n] = ldfrag(cur + 16384, wc * 64 + n * 16 + fr, kk * 4 + fq);
; #pragma unroll
;       for (int m = 0; m < 4; ++m)
; #pragma unroll
;         for (int n = 0; n < 4; ++n)
;           acc[m][n] = __builtin_amdgcn_mfma_f32_16x16x32_bf16(af[m], bfr[n], acc[m][n], 0, 0, 0);
;     }
;   }
; }
; DEVI void gate_tile(const Params& P, int l, int pm, int q, char* smem, int tid) {
;   const int nb = q >> 1, hb = q & 1;
;   const bfu* cb = (const bfu*)wsp(P, O_CB);
;   const bfu* A = cb + (long)pm * 128 * 1024 + nb * 128;
;   const bfu* Wa = (const bfu*)wsp(P, O_LRU) + nb * 16384 + hb * 64 * 128;
;   const bfu* Wx = Wa + 8 * 16384;
;   float* au0 = (float*)wsp(P, O_AU);
;   float* au1 = au0 + (long)8448 * 1024;
;   const float* ba = P.in[12] + l * 1024;
;   const float* bx = P.in[14] + l * 1024;
;   const float* lam = P.in[15] + l * 1024;
;   f32x4 acc[4][4]; ZERO_ACC(acc);
;   gemm_core_t<1>(acc, A, 1024, Wa, 128, 128, smem, tid, Wx);
;   epi_stage_f32(acc, smem, tid);
.LBB0_457:
	s_and_b64 vcc, exec, s[46:47]
	s_cbranch_vccz .LBB0_452
	s_bfe_u32 s54, s59, 0x30001
	s_mov_b64 s[62:63], 0x17d02000
	s_mov_b64 s[46:47], 0x2480000
	s_lshl_b32 s24, s54, 15
	v_lshl_add_u64 v[0:1], v[64:65], 0, s[46:47]
	v_lshl_add_u64 v[0:1], v[0:1], 0, s[24:25]
	s_lshl_b32 s24, s59, 6
	s_ashr_i32 s52, s59, 4
	s_and_b32 s60, s24, 64
	s_ashr_i32 s53, s52, 31
	s_lshl_b32 s24, s60, 8
	s_lshl_b64 s[64:65], s[52:53], 18
	v_lshl_add_u64 v[2:3], v[0:1], 0, s[24:25]
	v_lshl_add_u64 v[0:1], v[64:65], 0, s[62:63]
	v_lshl_add_u64 v[4:5], v[0:1], 0, s[64:65]
	s_lshl_b32 s24, s54, 8
	v_lshl_add_u64 v[4:5], v[4:5], 0, s[24:25]
	v_lshl_add_u64 v[8:9], v[22:23], 1, v[4:5]
	v_readfirstlane_b32 s24, v91
	s_mov_b64 s[46:47], 0x18d82000
	v_lshl_add_u64 v[8:9], v[8:9], 0, v[88:89]
	s_mov_b32 m0, s24
	v_lshl_add_u64 v[10:11], v[24:25], 1, v[4:5]
	v_mov_b32_e32 v43, v89
	v_readfirstlane_b32 s24, v102
	v_lshl_add_u64 v[6:7], v[2:3], 0, s[76:77]
	s_barrier
	global_load_lds_dwordx4 v[8:9], off
	v_lshl_add_u64 v[10:11], v[10:11], 0, v[42:43]
	s_mov_b32 m0, s24
	v_lshl_add_u64 v[12:13], v[26:27], 1, v[4:5]
	v_mov_b32_e32 v45, v89
	v_readfirstlane_b32 s24, v103
	global_load_lds_dwordx4 v[10:11], off
	v_lshl_add_u64 v[12:13], v[12:13], 0, v[44:45]
	s_mov_b32 m0, s24
	v_lshl_add_u64 v[4:5], v[28:29], 1, v[4:5]
	v_mov_b32_e32 v47, v89
	v_readfirstlane_b32 s24, v104
	v_cndmask_b32_e64 v15, v7, v3, s[40:41]
	v_cndmask_b32_e64 v14, v6, v2, s[40:41]
	v_add_u32_e32 v18, 0x4000, v91
	global_load_lds_dwordx4 v[12:13], off
	v_lshl_add_u64 v[4:5], v[4:5], 0, v[46:47]
	s_mov_b32 m0, s24
	v_lshl_add_u64 v[16:17], v[14:15], 0, v[30:31]
	v_readfirstlane_b32 s24, v18
	v_cndmask_b32_e64 v19, v3, v7, s[40:41]
	v_cndmask_b32_e64 v18, v2, v6, s[40:41]
	v_add_u32_e32 v41, 0x5000, v91
	global_load_lds_dwordx4 v[4:5], off
	v_lshl_add_u64 v[16:17], v[16:17], 0, v[88:89]
	s_mov_b32 m0, s24
	v_lshl_add_u64 v[18:19], v[18:19], 0, v[32:33]
	v_readfirstlane_b32 s24, v41
	v_add_u32_e32 v41, 0x6000, v91
	global_load_lds_dwordx4 v[16:17], off
	v_lshl_add_u64 v[18:19], v[18:19], 0, v[42:43]
	s_mov_b32 m0, s24
	v_lshl_add_u64 v[14:15], v[14:15], 0, v[34:35]
	v_readfirstlane_b32 s24, v41
	global_load_lds_dwordx4 v[18:19], off
	v_lshl_add_u64 v[14:15], v[14:15], 0, v[44:45]
	s_mov_b32 m0, s24
	v_cndmask_b32_e64 v3, v7, v3, s[42:43]
	v_cndmask_b32_e64 v2, v6, v2, s[42:43]
	v_add_u32_e32 v6, 0x7000, v91
	s_mov_b64 s[4:5], 0x80
	global_load_lds_dwordx4 v[14:15], off
	v_lshl_add_u64 v[2:3], v[2:3], 0, v[36:37]
	v_readfirstlane_b32 s24, v6
	v_lshl_add_u64 v[6:7], v[14:15], 0, s[4:5]
	v_lshl_add_u64 v[14:15], v[18:19], 0, s[4:5]
	v_add_u32_e32 v18, 0x8000, v91
	v_lshl_add_u64 v[2:3], v[2:3], 0, v[46:47]
	s_mov_b32 m0, s24
	v_readfirstlane_b32 s24, v18
	global_load_lds_dwordx4 v[2:3], off
	v_lshl_add_u64 v[8:9], v[8:9], 0, s[4:5]
	s_mov_b32 m0, s24
	s_waitcnt vmcnt(0)
	s_waitcnt vmcnt(0) lgkmcnt(0)
	s_barrier
	global_load_lds_dwordx4 v[8:9], off
	v_add_u32_e32 v8, 0x9000, v91
	v_lshl_add_u64 v[10:11], v[10:11], 0, s[4:5]
	v_readfirstlane_b32 s24, v8
	v_add_u32_e32 v8, 0xa000, v91
	s_mov_b32 m0, s24
	v_readfirstlane_b32 s24, v8
	v_add_u32_e32 v8, 0xb000, v91
	v_lshl_add_u64 v[12:13], v[12:13], 0, s[4:5]
	global_load_lds_dwordx4 v[10:11], off
	s_mov_b32 m0, s24
	v_readfirstlane_b32 s24, v8
	v_lshl_add_u64 v[4:5], v[4:5], 0, s[4:5]
	global_load_lds_dwordx4 v[12:13], off
	s_mov_b32 m0, s24
	v_lshl_add_u64 v[16:17], v[16:17], 0, s[4:5]
	global_load_lds_dwordx4 v[4:5], off
	v_add_u32_e32 v4, 0xc000, v91
	v_lshl_add_u64 v[2:3], v[2:3], 0, s[4:5]
	v_readfirstlane_b32 s24, v4
	v_add_u32_e32 v4, 0xd000, v91
	s_mov_b32 m0, s24
	v_readfirstlane_b32 s24, v4
	v_add_u32_e32 v4, 0xe000, v91
	global_load_lds_dwordx4 v[16:17], off
	s_mov_b32 m0, s24
	v_readfirstlane_b32 s24, v4
	v_add_u32_e32 v4, 0xf000, v91
	global_load_lds_dwordx4 v[14:15], off
	s_mov_b32 m0, s24
	v_readfirstlane_b32 s24, v4
	global_load_lds_dwordx4 v[6:7], off
	s_mov_b32 m0, s24
	v_add_u32_e32 v18, v105, v106
	global_load_lds_dwordx4 v[2:3], off
	ds_read_b128 v[2:5], v18
	ds_read_b128 v[114:117], v18 offset:2048
	ds_read_b128 v[130:133], v18 offset:4096
	ds_read_b128 v[146:149], v18 offset:6144
	v_add_u32_e32 v19, v105, v107
	ds_read_b128 v[6:9], v19 offset:16384
	ds_read_b128 v[14:17], v19 offset:18432
	ds_read_b128 v[52:55], v19 offset:20480
	ds_read_b128 v[60:63], v19 offset:22528
	v_add_u32_e32 v41, v108, v106
	ds_read_b128 v[150:153], v41
	v_add_u32_e32 v43, v108, v107
	s_waitcnt lgkmcnt(0)
	v_mfma_f32_16x16x32_bf16 v[10:13], v[2:5], v[6:9], 0
	ds_read_b128 v[154:157], v43 offset:18432
	ds_read_b128 v[158:161], v43 offset:20480
	ds_read_b128 v[162:165], v43 offset:22528
	v_mfma_f32_16x16x32_bf16 v[48:51], v[2:5], v[14:17], 0
	s_lshl_b32 s24, s54, 7
	s_lshl_b64 s[54:55], s[52:53], 17
	s_mov_b32 s61, 0
	v_mfma_f32_16x16x32_bf16 v[56:59], v[2:5], v[52:55], 0
	v_mfma_f32_16x16x32_bf16 v[2:5], v[2:5], v[60:63], 0
	v_mfma_f32_16x16x32_bf16 v[118:121], v[114:117], v[6:9], 0
	v_mfma_f32_16x16x32_bf16 v[122:125], v[114:117], v[14:17], 0
	v_mfma_f32_16x16x32_bf16 v[126:129], v[114:117], v[52:55], 0
	v_mfma_f32_16x16x32_bf16 v[114:117], v[114:117], v[60:63], 0
	v_mfma_f32_16x16x32_bf16 v[134:137], v[130:133], v[6:9], 0
	v_mfma_f32_16x16x32_bf16 v[138:141], v[130:133], v[14:17], 0
	v_mfma_f32_16x16x32_bf16 v[142:145], v[130:133], v[52:55], 0
	v_mfma_f32_16x16x32_bf16 v[130:133], v[130:133], v[60:63], 0
	v_mfma_f32_16x16x32_bf16 v[6:9], v[146:149], v[6:9], 0
	v_mfma_f32_16x16x32_bf16 v[14:17], v[146:149], v[14:17], 0
	v_mfma_f32_16x16x32_bf16 v[52:55], v[146:149], v[52:55], 0
	v_mfma_f32_16x16x32_bf16 v[60:63], v[146:149], v[60:63], 0
	ds_read_b128 v[146:149], v43 offset:16384
	s_waitcnt lgkmcnt(0)
	v_mfma_f32_16x16x32_bf16 v[10:13], v[150:153], v[146:149], v[10:13]
	v_mfma_f32_16x16x32_bf16 v[48:51], v[150:153], v[154:157], v[48:51]
	v_mfma_f32_16x16x32_bf16 v[56:59], v[150:153], v[158:161], v[56:59]
	v_mfma_f32_16x16x32_bf16 v[2:5], v[150:153], v[162:165], v[2:5]
	ds_read_b128 v[150:153], v41 offset:2048
	s_waitcnt lgkmcnt(0)
	v_mfma_f32_16x16x32_bf16 v[118:121], v[150:153], v[146:149], v[118:121]
	v_mfma_f32_16x16x32_bf16 v[122:125], v[150:153], v[154:157], v[122:125]
	v_mfma_f32_16x16x32_bf16 v[126:129], v[150:153], v[158:161], v[126:129]
	v_mfma_f32_16x16x32_bf16 v[114:117], v[150:153], v[162:165], v[114:117]
	ds_read_b128 v[150:153], v41 offset:4096
	s_waitcnt lgkmcnt(0)
	v_mfma_f32_16x16x32_bf16 v[134:137], v[150:153], v[146:149], v[134:137]
	v_mfma_f32_16x16x32_bf16 v[138:141], v[150:153], v[154:157], v[138:141]
	v_mfma_f32_16x16x32_bf16 v[142:145], v[150:153], v[158:161], v[142:145]
	v_mfma_f32_16x16x32_bf16 v[130:133], v[150:153], v[162:165], v[130:133]
	ds_read_b128 v[150:153], v41 offset:6144
	s_waitcnt vmcnt(0)
	s_waitcnt vmcnt(0) lgkmcnt(0)
	v_mfma_f32_16x16x32_bf16 v[6:9], v[150:153], v[146:149], v[6:9]
	s_barrier
; DEVI void epi_stage_f32(const f32x4 (&acc)[4][4], char* smem, int tid) {
;   const int wid = tid >> 6, lane = tid & 63, wr = wid >> 1, wc = wid & 1, fr = lane & 15, fq = lane >> 4;
;   float* T = reinterpret_cast<float*>(smem);
;   __syncthreads();
; #pragma unroll
;   for (int m = 0; m < 4; ++m)
; #pragma unroll
;     for (int n = 0; n < 4; ++n)
; #pragma unroll
;       for (int j = 0; j < 4; ++j)
;         T[(wr * 64 + m * 16 + fq * 4 + j) * 128 + wc * 64 + n * 16 + fr] = acc[m][n][j];
;   __syncthreads();
; }
; DEVI void gate_tile(const Params& P, int l, int pm, int q, char* smem, int tid) {
;     ...
;   gemm_core_t<1>(acc, A, 1024, Wa, 128, 128, smem, tid, Wx);
;   epi_stage_f32(acc, smem, tid);
;   const float* T = reinterpret_cast<const float*>(smem);
;   float* Tw = reinterpret_cast<float*>(smem);
; #pragma unroll 4
;   for (int q = 0; q < 8; ++q) {
;     const int id = tid + 256 * q, row = id >> 4, g4 = id & 15;
;     const int cl = g4 * 4, wcc = cl >> 5, c32 = cl & 31;
;     const long grow = (long)pm * 128 + row;
;     const int col = nb * 128 + hb * 64 + cl;
;     float4 rp = *reinterpret_cast<const float4*>(T + row * 128 + wcc * 64 + c32);
;     float4 gp = *reinterpret_cast<const float4*>(T + row * 128 + wcc * 64 + 32 + c32);
;     float xv[4], bav[4], bxv[4], lmv[4];
;     load4bf(cb + grow * 1024 + col, xv);
	ds_read_b128 v[146:149], v18 offset:32768
	v_mfma_f32_16x16x32_bf16 v[14:17], v[150:153], v[154:157], v[14:17]
	ds_read_b128 v[154:157], v19 offset:51200
	ds_read_b128 v[166:169], v41 offset:38912
	v_mfma_f32_16x16x32_bf16 v[52:55], v[150:153], v[158:161], v[52:55]
	ds_read_b128 v[158:161], v19 offset:53248
	v_mfma_f32_16x16x32_bf16 v[60:63], v[150:153], v[162:165], v[60:63]
	ds_read_b128 v[150:153], v19 offset:49152
	ds_read_b128 v[162:165], v19 offset:55296
	s_waitcnt lgkmcnt(1)
	v_mfma_f32_16x16x32_bf16 v[10:13], v[146:149], v[150:153], v[10:13]
	v_mfma_f32_16x16x32_bf16 v[48:51], v[146:149], v[154:157], v[48:51]
	v_mfma_f32_16x16x32_bf16 v[56:59], v[146:149], v[158:161], v[56:59]
	s_waitcnt lgkmcnt(0)
	v_mfma_f32_16x16x32_bf16 v[2:5], v[146:149], v[162:165], v[2:5]
	ds_read_b128 v[146:149], v18 offset:34816
	s_waitcnt lgkmcnt(0)
	v_mfma_f32_16x16x32_bf16 v[118:121], v[146:149], v[150:153], v[118:121]
	v_mfma_f32_16x16x32_bf16 v[122:125], v[146:149], v[154:157], v[122:125]
	v_mfma_f32_16x16x32_bf16 v[126:129], v[146:149], v[158:161], v[126:129]
	v_mfma_f32_16x16x32_bf16 v[114:117], v[146:149], v[162:165], v[114:117]
	ds_read_b128 v[146:149], v18 offset:36864
	s_waitcnt lgkmcnt(0)
	v_mfma_f32_16x16x32_bf16 v[134:137], v[146:149], v[150:153], v[134:137]
	v_mfma_f32_16x16x32_bf16 v[138:141], v[146:149], v[154:157], v[138:141]
	v_mfma_f32_16x16x32_bf16 v[142:145], v[146:149], v[158:161], v[142:145]
	v_mfma_f32_16x16x32_bf16 v[130:133], v[146:149], v[162:165], v[130:133]
	ds_read_b128 v[146:149], v18 offset:38912
	v_lshl_add_u64 v[18:19], v[64:65], 0, s[46:47]
	s_mov_b64 s[46:47], 0x2100000
	s_waitcnt lgkmcnt(0)
	v_mfma_f32_16x16x32_bf16 v[6:9], v[146:149], v[150:153], v[6:9]
	ds_read_b128 v[150:153], v41 offset:32768
	v_mfma_f32_16x16x32_bf16 v[14:17], v[146:149], v[154:157], v[14:17]
	ds_read_b128 v[154:157], v43 offset:51200
	v_mfma_f32_16x16x32_bf16 v[52:55], v[146:149], v[158:161], v[52:55]
	ds_read_b128 v[158:161], v43 offset:53248
	v_mfma_f32_16x16x32_bf16 v[60:63], v[146:149], v[162:165], v[60:63]
	ds_read_b128 v[146:149], v43 offset:49152
	ds_read_b128 v[162:165], v43 offset:55296
	s_waitcnt lgkmcnt(1)
	v_mfma_f32_16x16x32_bf16 v[10:13], v[150:153], v[146:149], v[10:13]
	v_mfma_f32_16x16x32_bf16 v[48:51], v[150:153], v[154:157], v[48:51]
	v_mfma_f32_16x16x32_bf16 v[56:59], v[150:153], v[158:161], v[56:59]
	s_waitcnt lgkmcnt(0)
	v_mfma_f32_16x16x32_bf16 v[2:5], v[150:153], v[162:165], v[2:5]
	ds_read_b128 v[150:153], v41 offset:34816
	s_waitcnt lgkmcnt(0)
	v_mfma_f32_16x16x32_bf16 v[118:121], v[150:153], v[146:149], v[118:121]
	v_mfma_f32_16x16x32_bf16 v[122:125], v[150:153], v[154:157], v[122:125]
	v_mfma_f32_16x16x32_bf16 v[126:129], v[150:153], v[158:161], v[126:129]
	v_mfma_f32_16x16x32_bf16 v[114:117], v[150:153], v[162:165], v[114:117]
	ds_read_b128 v[150:153], v41 offset:36864
	v_add_u32_e32 v41, 0x400, v109
	s_waitcnt lgkmcnt(0)
	v_mfma_f32_16x16x32_bf16 v[134:137], v[150:153], v[146:149], v[134:137]
	s_barrier
	ds_write2_b32 v109, v10, v48 offset1:16
	ds_write2_b32 v109, v11, v49 offset0:128 offset1:144
	v_mfma_f32_16x16x32_bf16 v[138:141], v[150:153], v[154:157], v[138:141]
	ds_write2_b32 v41, v12, v50 offset1:16
	ds_write2_b32 v41, v13, v51 offset0:128 offset1:144
	ds_write2_b32 v109, v56, v2 offset0:32 offset1:48
	ds_write2_b32 v109, v57, v3 offset0:160 offset1:176
	ds_write2_b32 v41, v58, v4 offset0:32 offset1:48
	v_add_u32_e32 v2, 0x2000, v109
	v_mfma_f32_16x16x32_bf16 v[6:9], v[166:169], v[146:149], v[6:9]
	v_add_u32_e32 v3, 0x2400, v109
	ds_write2_b32 v41, v59, v5 offset0:160 offset1:176
	ds_write2_b32 v2, v118, v122 offset1:16
	ds_write2_b32 v2, v119, v123 offset0:128 offset1:144
	v_mfma_f32_16x16x32_bf16 v[14:17], v[166:169], v[154:157], v[14:17]
	ds_write2_b32 v3, v120, v124 offset1:16
	ds_write2_b32 v3, v121, v125 offset0:128 offset1:144
	ds_write2_b32 v2, v126, v114 offset0:32 offset1:48
	ds_write2_b32 v2, v127, v115 offset0:160 offset1:176
	ds_write2_b32 v3, v128, v116 offset0:32 offset1:48
	ds_write2_b32 v3, v129, v117 offset0:160 offset1:176
	v_add_u32_e32 v2, 0x4000, v109
	v_add_u32_e32 v3, 0x4400, v109
	v_mfma_f32_16x16x32_bf16 v[142:145], v[150:153], v[158:161], v[142:145]
	ds_write2_b32 v2, v134, v138 offset1:16
	ds_write2_b32 v2, v135, v139 offset0:128 offset1:144
	v_mfma_f32_16x16x32_bf16 v[130:133], v[150:153], v[162:165], v[130:133]
	ds_write2_b32 v3, v136, v140 offset1:16
	ds_write2_b32 v3, v137, v141 offset0:128 offset1:144
	s_nop 5
	ds_write2_b32 v2, v142, v130 offset0:32 offset1:48
	ds_write2_b32 v2, v143, v131 offset0:160 offset1:176
	ds_write2_b32 v3, v144, v132 offset0:32 offset1:48
	ds_write2_b32 v3, v145, v133 offset0:160 offset1:176
	v_add_u32_e32 v2, 0x6000, v109
	v_mfma_f32_16x16x32_bf16 v[10:13], v[166:169], v[158:161], v[52:55]
	v_add_u32_e32 v3, 0x6400, v109
	ds_write2_b32 v2, v6, v14 offset1:16
	ds_write2_b32 v2, v7, v15 offset0:128 offset1:144
	v_mfma_f32_16x16x32_bf16 v[48:51], v[166:169], v[162:165], v[60:63]
	ds_write2_b32 v3, v8, v16 offset1:16
	ds_write2_b32 v3, v9, v17 offset0:128 offset1:144
	s_nop 5
	ds_write2_b32 v2, v10, v48 offset0:32 offset1:48
	ds_write2_b32 v2, v11, v49 offset0:160 offset1:176
	ds_write2_b32 v3, v12, v50 offset0:32 offset1:48
	ds_write2_b32 v3, v13, v51 offset0:160 offset1:176
	v_or_b32_e32 v2, s60, v110
	v_or_b32_e32 v4, s24, v2
	v_lshlrev_b32_e32 v2, 1, v4
	v_mov_b32_e32 v3, v89
	v_lshl_add_u64 v[48:49], v[0:1], 0, v[2:3]
	v_lshlrev_b32_e32 v0, 2, v4
	v_mov_b32_e32 v1, v89
	v_lshl_add_u64 v[56:57], v[18:19], 0, v[0:1]
	v_lshl_add_u64 v[50:51], s[26:27], 0, v[0:1]
	v_lshl_add_u64 v[52:53], s[48:49], 0, v[0:1]
	v_lshl_add_u64 v[54:55], s[50:51], 0, v[0:1]
	v_lshl_add_u64 v[58:59], v[56:57], 0, s[46:47]
	s_waitcnt lgkmcnt(0)
	s_barrier
; DEVI float sigmoidf_(float x) { return 1.f / (1.f + __expf(-x)); }
; DEVI void gate_tile(const Params& P, int l, int pm, int q, char* smem, int tid) {
;     ...
;     ld4f(ba + col, bav); ld4f(bx + col, bxv); ld4f(lam + col, lmv);
;     const float rpa[4] = {rp.x, rp.y, rp.z, rp.w}, gpa[4] = {gp.x, gp.y, gp.z, gp.w};
;     float av[4], uv[4];
; #pragma unroll
;     for (int i = 0; i < 4; ++i) {
;       float r = sigmoidf_(rpa[i] + bav[i]);
;       float gi = sigmoidf_(gpa[i] + bxv[i]);
;       float a = __expf(-8.f * log1pf(__expf(-lmv[i])) * r);
	global_load_dwordx4 v[244:247], v[54:55], off
	s_waitcnt vmcnt(0)
	v_mul_f32_e32 v198, 0xbfb8aa3b, v244
	v_exp_f32_e32 v198, v198
	s_nop 0
	v_add_f32_e32 v244, 1.0, v198
	v_add_f32_e32 v199, -1.0, v244
	v_sub_f32_e32 v200, v199, v244
	v_add_f32_e32 v200, 1.0, v200
	v_sub_f32_e32 v199, v198, v199
	v_add_f32_e32 v199, v199, v200
	v_frexp_mant_f32_e32 v200, v244
	v_cvt_f64_f32_e32 v[196:197], v244
	v_cmp_gt_f32_e32 vcc, s7, v200
	v_frexp_exp_i32_f64_e32 v200, v[196:197]
	s_nop 0
	v_subbrev_co_u32_e32 v200, vcc, 0, v200, vcc
	v_sub_u32_e32 v201, 0, v200
	v_ldexp_f32 v244, v244, v201
	v_ldexp_f32 v199, v199, v201
	v_add_f32_e32 v201, -1.0, v244
	v_add_f32_e32 v202, 1.0, v201
	v_sub_f32_e32 v202, v244, v202
	v_add_f32_e32 v202, v199, v202
	v_add_f32_e32 v196, v201, v202
	v_sub_f32_e32 v201, v196, v201
	v_sub_f32_e32 v201, v202, v201
	v_add_f32_e32 v202, 1.0, v244
	v_add_f32_e32 v197, -1.0, v202
	v_sub_f32_e32 v244, v244, v197
	v_add_f32_e32 v244, v199, v244
	v_add_f32_e32 v199, v202, v244
	v_sub_f32_e32 v202, v199, v202
	v_sub_f32_e32 v244, v244, v202
	v_rcp_f32_e32 v202, v199
	v_cvt_f32_i32_e32 v200, v200
	v_cmp_neq_f32_e32 vcc, s20, v198
	v_mul_f32_e32 v197, v196, v202
	v_mul_f32_e32 v203, v199, v197
	v_fma_f32 v204, v197, v199, -v203
	v_fmac_f32_e32 v204, v197, v244
	v_add_f32_e32 v205, v203, v204
	v_sub_f32_e32 v206, v196, v205
	v_sub_f32_e32 v196, v196, v206
	v_sub_f32_e32 v203, v205, v203
	v_sub_f32_e32 v196, v196, v205
	v_add_f32_e32 v201, v201, v196
	v_sub_f32_e32 v196, v203, v204
	v_add_f32_e32 v201, v196, v201
	v_add_f32_e32 v196, v206, v201
	v_mul_f32_e32 v203, v202, v196
	v_mul_f32_e32 v204, v199, v203
	v_fma_f32 v199, v203, v199, -v204
	v_fmac_f32_e32 v199, v203, v244
	v_sub_f32_e32 v244, v206, v196
	v_add_f32_e32 v244, v201, v244
	v_add_f32_e32 v201, v204, v199
	v_sub_f32_e32 v205, v196, v201
	v_sub_f32_e32 v196, v196, v205
	v_sub_f32_e32 v204, v201, v204
	v_sub_f32_e32 v201, v196, v201
	v_add_f32_e32 v244, v244, v201
	v_sub_f32_e32 v199, v204, v199
	v_add_f32_e32 v244, v199, v244
	v_add_f32_e32 v199, v197, v203
	v_add_f32_e32 v244, v205, v244
	v_sub_f32_e32 v201, v199, v197
	v_mul_f32_e32 v244, v202, v244
	v_sub_f32_e32 v201, v203, v201
	v_add_f32_e32 v244, v201, v244
	v_mul_f32_e32 v197, 0x3f317218, v200
	v_add_f32_e32 v201, v199, v244
	v_fma_f32 v203, v200, s10, -v197
	v_mul_f32_e32 v202, v201, v201
	v_fmac_f32_e32 v203, 0xb102e308, v200
	v_sub_f32_e32 v199, v201, v199
	v_fmamk_f32 v196, v202, 0x3e9b6dac, v185
	v_sub_f32_e32 v244, v244, v199
	v_add_f32_e32 v199, v197, v203
	v_fmaak_f32 v196, v202, v196, 0x3f2aaada
	v_sub_f32_e32 v200, v199, v197
	v_ldexp_f32 v197, v201, 1
	v_mul_f32_e32 v201, v201, v202
	v_mul_f32_e32 v201, v201, v196
	v_add_f32_e32 v202, v197, v201
	v_sub_f32_e32 v196, v202, v197
	v_ldexp_f32 v244, v244, 1
	v_sub_f32_e32 v201, v201, v196
	v_add_f32_e32 v244, v244, v201
	v_add_f32_e32 v201, v202, v244
	v_sub_f32_e32 v202, v201, v202
	v_sub_f32_e32 v244, v244, v202
	v_add_f32_e32 v202, v199, v201
	v_sub_f32_e32 v196, v202, v199
	v_sub_f32_e32 v197, v202, v196
	v_sub_f32_e32 v200, v203, v200
	v_sub_f32_e32 v199, v199, v197
	v_sub_f32_e32 v201, v201, v196
	v_add_f32_e32 v199, v201, v199
	v_add_f32_e32 v201, v200, v244
	v_sub_f32_e32 v196, v201, v200
	v_sub_f32_e32 v197, v201, v196
	v_sub_f32_e32 v200, v200, v197
	v_sub_f32_e32 v244, v244, v196
	v_add_f32_e32 v199, v201, v199
	v_add_f32_e32 v244, v244, v200
	v_add_f32_e32 v200, v202, v199
	v_sub_f32_e32 v201, v200, v202
	v_sub_f32_e32 v199, v199, v201
	v_add_f32_e32 v244, v244, v199
	v_add_f32_e32 v244, v200, v244
	v_cndmask_b32_e32 v244, v189, v244, vcc
	v_cmp_ngt_f32_e32 vcc, -1.0, v198
	s_nop 1
	v_cndmask_b32_e32 v244, v194, v244, vcc
	v_cmp_neq_f32_e32 vcc, -1.0, v198
	s_nop 1
	v_cndmask_b32_e32 v244, v195, v244, vcc
	v_cmp_lt_f32_e64 vcc, |v198|, s11
	s_nop 1
	v_cndmask_b32_e32 v198, v244, v198, vcc
	v_mul_f32_e32 v198, 0xc1000000, v198
	v_mov_b32_e32 v240, v198
	v_mul_f32_e32 v198, 0xbfb8aa3b, v245
	v_exp_f32_e32 v198, v198
	s_nop 0
	v_add_f32_e32 v245, 1.0, v198
	v_add_f32_e32 v196, -1.0, v245
	v_sub_f32_e32 v197, v196, v245
	v_add_f32_e32 v197, 1.0, v197
	v_sub_f32_e32 v196, v198, v196
	v_add_f32_e32 v199, v196, v197
	v_frexp_mant_f32_e32 v196, v245
	v_cmp_gt_f32_e32 vcc, s7, v196
	v_cvt_f64_f32_e32 v[196:197], v245
	v_frexp_exp_i32_f64_e32 v196, v[196:197]
	v_subbrev_co_u32_e32 v196, vcc, 0, v196, vcc
	v_sub_u32_e32 v197, 0, v196
	v_ldexp_f32 v245, v245, v197
	v_ldexp_f32 v197, v199, v197
	v_add_f32_e32 v199, -1.0, v245
	v_add_f32_e32 v200, 1.0, v199
	v_sub_f32_e32 v200, v245, v200
	v_add_f32_e32 v200, v197, v200
	v_add_f32_e32 v201, v199, v200
	v_sub_f32_e32 v199, v201, v199
	v_sub_f32_e32 v199, v200, v199
	v_add_f32_e32 v200, 1.0, v245
	v_add_f32_e32 v202, -1.0, v200
	v_sub_f32_e32 v245, v245, v202
	v_add_f32_e32 v245, v197, v245
	v_add_f32_e32 v197, v200, v245
	v_sub_f32_e32 v200, v197, v200
	v_sub_f32_e32 v245, v245, v200
	v_rcp_f32_e32 v200, v197
	v_cvt_f32_i32_e32 v196, v196
	v_cmp_neq_f32_e32 vcc, s20, v198
	v_mul_f32_e32 v202, v201, v200
	v_mul_f32_e32 v203, v197, v202
	v_fma_f32 v204, v202, v197, -v203
	v_fmac_f32_e32 v204, v202, v245
	v_add_f32_e32 v205, v203, v204
	v_sub_f32_e32 v206, v201, v205
	v_sub_f32_e32 v201, v201, v206
	v_sub_f32_e32 v203, v205, v203
	v_sub_f32_e32 v201, v201, v205
	v_add_f32_e32 v199, v199, v201
	v_sub_f32_e32 v201, v203, v204
	v_add_f32_e32 v199, v201, v199
	v_add_f32_e32 v201, v206, v199
	v_mul_f32_e32 v203, v200, v201
	v_mul_f32_e32 v204, v197, v203
	v_fma_f32 v197, v203, v197, -v204
	v_fmac_f32_e32 v197, v203, v245
	v_sub_f32_e32 v245, v206, v201
	v_add_f32_e32 v245, v199, v245
	v_add_f32_e32 v199, v204, v197
; DEVI float sigmoidf_(float x) { return 1.f / (1.f + __expf(-x)); }
; DEVI void gate_tile(const Params& P, int l, int pm, int q, char* smem, int tid) {
;     ...
;       float r = sigmoidf_(rpa[i] + bav[i]);
;       float gi = sigmoidf_(gpa[i] + bxv[i]);
;       float a = __expf(-8.f * log1pf(__expf(-lmv[i])) * r);
	v_sub_f32_e32 v205, v201, v199
	v_sub_f32_e32 v201, v201, v205
	v_sub_f32_e32 v204, v199, v204
	v_sub_f32_e32 v199, v201, v199
	v_add_f32_e32 v245, v245, v199
	v_sub_f32_e32 v197, v204, v197
	v_add_f32_e32 v245, v197, v245
	v_add_f32_e32 v197, v202, v203
	v_add_f32_e32 v245, v205, v245
	v_sub_f32_e32 v199, v197, v202
	v_mul_f32_e32 v245, v200, v245
	v_sub_f32_e32 v199, v203, v199
	v_add_f32_e32 v245, v199, v245
	v_mul_f32_e32 v202, 0x3f317218, v196
	v_add_f32_e32 v199, v197, v245
	v_fma_f32 v203, v196, s10, -v202
	v_mul_f32_e32 v200, v199, v199
	v_fmac_f32_e32 v203, 0xb102e308, v196
	v_sub_f32_e32 v196, v199, v197
	v_fmamk_f32 v201, v200, 0x3e9b6dac, v185
	v_sub_f32_e32 v245, v245, v196
	v_add_f32_e32 v196, v202, v203
	v_fmaak_f32 v201, v200, v201, 0x3f2aaada
	v_sub_f32_e32 v197, v196, v202
	v_ldexp_f32 v202, v199, 1
	v_mul_f32_e32 v199, v199, v200
	v_mul_f32_e32 v199, v199, v201
	v_add_f32_e32 v200, v202, v199
	v_sub_f32_e32 v201, v200, v202
	v_ldexp_f32 v245, v245, 1
	v_sub_f32_e32 v199, v199, v201
	v_add_f32_e32 v245, v245, v199
	v_add_f32_e32 v199, v200, v245
	v_sub_f32_e32 v200, v199, v200
	v_sub_f32_e32 v245, v245, v200
	v_add_f32_e32 v200, v196, v199
	v_sub_f32_e32 v201, v200, v196
	v_sub_f32_e32 v202, v200, v201
	v_sub_f32_e32 v197, v203, v197
	v_sub_f32_e32 v196, v196, v202
	v_sub_f32_e32 v199, v199, v201
	v_add_f32_e32 v196, v199, v196
	v_add_f32_e32 v199, v197, v245
	v_sub_f32_e32 v201, v199, v197
	v_sub_f32_e32 v202, v199, v201
	v_sub_f32_e32 v197, v197, v202
	v_sub_f32_e32 v245, v245, v201
	v_add_f32_e32 v196, v199, v196
	v_add_f32_e32 v245, v245, v197
	v_add_f32_e32 v197, v200, v196
	v_sub_f32_e32 v199, v197, v200
	v_sub_f32_e32 v196, v196, v199
	v_add_f32_e32 v245, v245, v196
	v_add_f32_e32 v245, v197, v245
	v_cndmask_b32_e32 v245, v189, v245, vcc
	v_cmp_ngt_f32_e32 vcc, -1.0, v198
	s_nop 1
	v_cndmask_b32_e32 v245, v194, v245, vcc
	v_cmp_neq_f32_e32 vcc, -1.0, v198
	s_nop 1
	v_cndmask_b32_e32 v245, v195, v245, vcc
	v_cmp_lt_f32_e64 vcc, |v198|, s11
	s_nop 1
	v_cndmask_b32_e32 v198, v245, v198, vcc
	v_mul_f32_e32 v198, 0xc1000000, v198
	v_mov_b32_e32 v241, v198
	v_mul_f32_e32 v198, 0xbfb8aa3b, v246
	v_exp_f32_e32 v198, v198
	s_nop 0
	v_add_f32_e32 v246, 1.0, v198
	v_add_f32_e32 v196, -1.0, v246
	v_sub_f32_e32 v197, v196, v246
	v_add_f32_e32 v197, 1.0, v197
	v_sub_f32_e32 v196, v198, v196
	v_add_f32_e32 v199, v196, v197
	v_frexp_mant_f32_e32 v196, v246
	v_cmp_gt_f32_e32 vcc, s7, v196
	v_cvt_f64_f32_e32 v[196:197], v246
	v_frexp_exp_i32_f64_e32 v196, v[196:197]
	v_subbrev_co_u32_e32 v196, vcc, 0, v196, vcc
	v_sub_u32_e32 v197, 0, v196
	v_ldexp_f32 v246, v246, v197
	v_ldexp_f32 v197, v199, v197
	v_add_f32_e32 v199, -1.0, v246
	v_add_f32_e32 v200, 1.0, v199
	v_sub_f32_e32 v200, v246, v200
	v_add_f32_e32 v200, v197, v200
	v_add_f32_e32 v201, v199, v200
	v_sub_f32_e32 v199, v201, v199
	v_sub_f32_e32 v199, v200, v199
	v_add_f32_e32 v200, 1.0, v246
	v_add_f32_e32 v202, -1.0, v200
	v_sub_f32_e32 v246, v246, v202
	v_add_f32_e32 v246, v197, v246
	v_add_f32_e32 v197, v200, v246
	v_sub_f32_e32 v200, v197, v200
	v_sub_f32_e32 v246, v246, v200
	v_rcp_f32_e32 v200, v197
	v_cvt_f32_i32_e32 v196, v196
	v_cmp_neq_f32_e32 vcc, s20, v198
	v_mul_f32_e32 v202, v201, v200
	v_mul_f32_e32 v203, v197, v202
	v_fma_f32 v204, v202, v197, -v203
	v_fmac_f32_e32 v204, v202, v246
	v_add_f32_e32 v205, v203, v204
	v_sub_f32_e32 v206, v201, v205
	v_sub_f32_e32 v201, v201, v206
	v_sub_f32_e32 v203, v205, v203
	v_sub_f32_e32 v201, v201, v205
	v_add_f32_e32 v199, v199, v201
	v_sub_f32_e32 v201, v203, v204
	v_add_f32_e32 v199, v201, v199
	v_add_f32_e32 v201, v206, v199
	v_mul_f32_e32 v203, v200, v201
	v_mul_f32_e32 v204, v197, v203
	v_fma_f32 v197, v203, v197, -v204
	v_fmac_f32_e32 v197, v203, v246
	v_sub_f32_e32 v246, v206, v201
	v_add_f32_e32 v246, v199, v246
	v_add_f32_e32 v199, v204, v197
	v_sub_f32_e32 v205, v201, v199
	v_sub_f32_e32 v201, v201, v205
	v_sub_f32_e32 v204, v199, v204
	v_sub_f32_e32 v199, v201, v199
	v_add_f32_e32 v246, v246, v199
	v_sub_f32_e32 v197, v204, v197
	v_add_f32_e32 v246, v197, v246
	v_add_f32_e32 v197, v202, v203
	v_add_f32_e32 v246, v205, v246
	v_sub_f32_e32 v199, v197, v202
	v_mul_f32_e32 v246, v200, v246
	v_sub_f32_e32 v199, v203, v199
	v_add_f32_e32 v246, v199, v246
	v_mul_f32_e32 v202, 0x3f317218, v196
	v_add_f32_e32 v199, v197, v246
	v_fma_f32 v203, v196, s10, -v202
	v_mul_f32_e32 v200, v199, v199
	v_fmac_f32_e32 v203, 0xb102e308, v196
	v_sub_f32_e32 v196, v199, v197
	v_fmamk_f32 v201, v200, 0x3e9b6dac, v185
	v_sub_f32_e32 v246, v246, v196
	v_add_f32_e32 v196, v202, v203
	v_fmaak_f32 v201, v200, v201, 0x3f2aaada
	v_sub_f32_e32 v197, v196, v202
	v_ldexp_f32 v202, v199, 1
	v_mul_f32_e32 v199, v199, v200
	v_mul_f32_e32 v199, v199, v201
	v_add_f32_e32 v200, v202, v199
	v_sub_f32_e32 v201, v200, v202
	v_ldexp_f32 v246, v246, 1
	v_sub_f32_e32 v199, v199, v201
	v_add_f32_e32 v246, v246, v199
	v_add_f32_e32 v199, v200, v246
	v_sub_f32_e32 v200, v199, v200
	v_sub_f32_e32 v246, v246, v200
	v_add_f32_e32 v200, v196, v199
	v_sub_f32_e32 v201, v200, v196
	v_sub_f32_e32 v202, v200, v201
	v_sub_f32_e32 v197, v203, v197
	v_sub_f32_e32 v196, v196, v202
	v_sub_f32_e32 v199, v199, v201
	v_add_f32_e32 v196, v199, v196
	v_add_f32_e32 v199, v197, v246
	v_sub_f32_e32 v201, v199, v197
	v_sub_f32_e32 v202, v199, v201
	v_sub_f32_e32 v197, v197, v202
	v_sub_f32_e32 v246, v246, v201
	v_add_f32_e32 v196, v199, v196
	v_add_f32_e32 v246, v246, v197
	v_add_f32_e32 v197, v200, v196
	v_sub_f32_e32 v199, v197, v200
	v_sub_f32_e32 v196, v196, v199
	v_add_f32_e32 v246, v246, v196
	v_add_f32_e32 v246, v197, v246
	v_cndmask_b32_e32 v246, v189, v246, vcc
; DEVI float sigmoidf_(float x) { return 1.f / (1.f + __expf(-x)); }
; DEVI void gate_tile(const Params& P, int l, int pm, int q, char* smem, int tid) {
;     ...
;     const int id = tid + 256 * q, row = id >> 4, g4 = id & 15;
;     const int cl = g4 * 4, wcc = cl >> 5, c32 = cl & 31;
;     const long grow = (long)pm * 128 + row;
;     const int col = nb * 128 + hb * 64 + cl;
;     float4 rp = *reinterpret_cast<const float4*>(T + row * 128 + wcc * 64 + c32);
;     float4 gp = *reinterpret_cast<const float4*>(T + row * 128 + wcc * 64 + 32 + c32);
;     float xv[4], bav[4], bxv[4], lmv[4];
;     load4bf(cb + grow * 1024 + col, xv);
;     ld4f(ba + col, bav); ld4f(bx + col, bxv); ld4f(lam + col, lmv);
;     const float rpa[4] = {rp.x, rp.y, rp.z, rp.w}, gpa[4] = {gp.x, gp.y, gp.z, gp.w};
;     float av[4], uv[4];
; #pragma unroll
;     for (int i = 0; i < 4; ++i) {
;       float r = sigmoidf_(rpa[i] + bav[i]);
;       float gi = sigmoidf_(gpa[i] + bxv[i]);
;       float a = __expf(-8.f * log1pf(__expf(-lmv[i])) * r);
	v_cmp_ngt_f32_e32 vcc, -1.0, v198
	s_nop 1
	v_cndmask_b32_e32 v246, v194, v246, vcc
	v_cmp_neq_f32_e32 vcc, -1.0, v198
	s_nop 1
	v_cndmask_b32_e32 v246, v195, v246, vcc
	v_cmp_lt_f32_e64 vcc, |v198|, s11
	s_nop 1
	v_cndmask_b32_e32 v198, v246, v198, vcc
	v_mul_f32_e32 v198, 0xc1000000, v198
	v_mov_b32_e32 v242, v198
	v_mul_f32_e32 v198, 0xbfb8aa3b, v247
	v_exp_f32_e32 v198, v198
	s_nop 0
	v_add_f32_e32 v247, 1.0, v198
	v_add_f32_e32 v196, -1.0, v247
	v_sub_f32_e32 v197, v196, v247
	v_add_f32_e32 v197, 1.0, v197
	v_sub_f32_e32 v196, v198, v196
	v_add_f32_e32 v199, v196, v197
	v_frexp_mant_f32_e32 v196, v247
	v_cmp_gt_f32_e32 vcc, s7, v196
	v_cvt_f64_f32_e32 v[196:197], v247
	v_frexp_exp_i32_f64_e32 v196, v[196:197]
	v_subbrev_co_u32_e32 v196, vcc, 0, v196, vcc
	v_sub_u32_e32 v197, 0, v196
	v_ldexp_f32 v247, v247, v197
	v_ldexp_f32 v197, v199, v197
	v_add_f32_e32 v199, -1.0, v247
	v_add_f32_e32 v200, 1.0, v199
	v_sub_f32_e32 v200, v247, v200
	v_add_f32_e32 v200, v197, v200
	v_add_f32_e32 v201, v199, v200
	v_sub_f32_e32 v199, v201, v199
	v_sub_f32_e32 v199, v200, v199
	v_add_f32_e32 v200, 1.0, v247
	v_add_f32_e32 v202, -1.0, v200
	v_sub_f32_e32 v247, v247, v202
	v_add_f32_e32 v247, v197, v247
	v_add_f32_e32 v197, v200, v247
	v_sub_f32_e32 v200, v197, v200
	v_sub_f32_e32 v247, v247, v200
	v_rcp_f32_e32 v200, v197
	v_cvt_f32_i32_e32 v196, v196
	v_cmp_neq_f32_e32 vcc, s20, v198
	v_mul_f32_e32 v202, v201, v200
	v_mul_f32_e32 v203, v197, v202
	v_fma_f32 v204, v202, v197, -v203
	v_fmac_f32_e32 v204, v202, v247
	v_add_f32_e32 v205, v203, v204
	v_sub_f32_e32 v206, v201, v205
	v_sub_f32_e32 v201, v201, v206
	v_sub_f32_e32 v203, v205, v203
	v_sub_f32_e32 v201, v201, v205
	v_add_f32_e32 v199, v199, v201
	v_sub_f32_e32 v201, v203, v204
	v_add_f32_e32 v199, v201, v199
	v_add_f32_e32 v201, v206, v199
	v_mul_f32_e32 v203, v200, v201
	v_mul_f32_e32 v204, v197, v203
	v_fma_f32 v197, v203, v197, -v204
	v_fmac_f32_e32 v197, v203, v247
	v_sub_f32_e32 v247, v206, v201
	v_add_f32_e32 v247, v199, v247
	v_add_f32_e32 v199, v204, v197
	v_sub_f32_e32 v205, v201, v199
	v_sub_f32_e32 v201, v201, v205
	v_sub_f32_e32 v204, v199, v204
	v_sub_f32_e32 v199, v201, v199
	v_add_f32_e32 v247, v247, v199
	v_sub_f32_e32 v197, v204, v197
	v_add_f32_e32 v247, v197, v247
	v_add_f32_e32 v197, v202, v203
	v_add_f32_e32 v247, v205, v247
	v_sub_f32_e32 v199, v197, v202
	v_mul_f32_e32 v247, v200, v247
	v_sub_f32_e32 v199, v203, v199
	v_add_f32_e32 v247, v199, v247
	v_mul_f32_e32 v202, 0x3f317218, v196
	v_add_f32_e32 v199, v197, v247
	v_fma_f32 v203, v196, s10, -v202
	v_mul_f32_e32 v200, v199, v199
	v_fmac_f32_e32 v203, 0xb102e308, v196
	v_sub_f32_e32 v196, v199, v197
	v_fmamk_f32 v201, v200, 0x3e9b6dac, v185
	v_sub_f32_e32 v247, v247, v196
	v_add_f32_e32 v196, v202, v203
	v_fmaak_f32 v201, v200, v201, 0x3f2aaada
	v_sub_f32_e32 v197, v196, v202
	v_ldexp_f32 v202, v199, 1
	v_mul_f32_e32 v199, v199, v200
	v_mul_f32_e32 v199, v199, v201
	v_add_f32_e32 v200, v202, v199
	v_sub_f32_e32 v201, v200, v202
	v_ldexp_f32 v247, v247, 1
	v_sub_f32_e32 v199, v199, v201
	v_add_f32_e32 v247, v247, v199
	v_add_f32_e32 v199, v200, v247
	v_sub_f32_e32 v200, v199, v200
	v_sub_f32_e32 v247, v247, v200
	v_add_f32_e32 v200, v196, v199
	v_sub_f32_e32 v201, v200, v196
	v_sub_f32_e32 v202, v200, v201
	v_sub_f32_e32 v197, v203, v197
	v_sub_f32_e32 v196, v196, v202
	v_sub_f32_e32 v199, v199, v201
	v_add_f32_e32 v196, v199, v196
	v_add_f32_e32 v199, v197, v247
	v_sub_f32_e32 v201, v199, v197
	v_sub_f32_e32 v202, v199, v201
	v_sub_f32_e32 v197, v197, v202
	v_sub_f32_e32 v247, v247, v201
	v_add_f32_e32 v196, v199, v196
	v_add_f32_e32 v247, v247, v197
	v_add_f32_e32 v197, v200, v196
	v_sub_f32_e32 v199, v197, v200
	v_sub_f32_e32 v196, v196, v199
	v_add_f32_e32 v247, v247, v196
	v_add_f32_e32 v247, v197, v247
	v_cndmask_b32_e32 v247, v189, v247, vcc
	v_cmp_ngt_f32_e32 vcc, -1.0, v198
	s_nop 1
	v_cndmask_b32_e32 v247, v194, v247, vcc
	v_cmp_neq_f32_e32 vcc, -1.0, v198
	s_nop 1
	v_cndmask_b32_e32 v247, v195, v247, vcc
	v_cmp_lt_f32_e64 vcc, |v198|, s11
	s_nop 1
	v_cndmask_b32_e32 v198, v247, v198, vcc
	v_mul_f32_e32 v198, 0xc1000000, v198
	v_mov_b32_e32 v243, v198
.LBB0_459:
	v_add_u32_e32 v41, s61, v20
	v_ashrrev_i32_e32 v8, 4, v41
	v_ashrrev_i32_e32 v9, 31, v8
	v_lshl_or_b32 v43, v8, 9, v112
	v_lshlrev_b64 v[8:9], 10, v[8:9]
	v_lshl_add_u64 v[100:101], v[8:9], 0, s[54:55]
	v_lshl_add_u64 v[8:9], v[100:101], 1, v[48:49]
	ds_read_b128 v[4:7], v43
	ds_read_b128 v[0:3], v43 offset:128
	global_load_dwordx2 v[8:9], v[8:9], off
	s_addk_i32 s61, 0x400
	s_cmpk_eq_i32 s61, 0x800
	s_waitcnt vmcnt(0)
	v_lshlrev_b32_e32 v62, 16, v8
	v_and_b32_e32 v63, 0xffff0000, v8
	v_lshlrev_b32_e32 v60, 16, v9
	v_and_b32_e32 v61, 0xffff0000, v9
	global_load_dwordx4 v[16:19], v[50:51], off
	global_load_dwordx4 v[12:15], v[52:53], off
	global_load_dwordx4 v[8:11], v[54:55], off
	s_waitcnt vmcnt(2) lgkmcnt(1)
	v_add_f32_e32 v4, v4, v16
	v_mul_f32_e32 v4, 0xbfb8aa3b, v4
	v_exp_f32_e32 v4, v4
	s_waitcnt vmcnt(1) lgkmcnt(0)
	v_add_f32_e32 v0, v0, v12
	v_mul_f32_e32 v0, 0xbfb8aa3b, v0
	v_add_f32_e32 v5, v5, v17
	v_add_f32_e32 v4, 1.0, v4
	v_div_scale_f32 v16, s[46:47], v4, v4, 1.0
	v_rcp_f32_e32 v45, v16
	v_mul_f32_e32 v5, 0xbfb8aa3b, v5
	v_exp_f32_e32 v5, v5
	v_add_f32_e32 v1, v1, v13
	v_fma_f32 v47, -v16, v45, 1.0
	v_fmac_f32_e32 v45, v47, v45
	v_div_scale_f32 v47, vcc, 1.0, v4, 1.0
	v_mul_f32_e32 v113, v47, v45
	v_fma_f32 v114, -v16, v113, v47
	v_fmac_f32_e32 v113, v114, v45
	v_fma_f32 v16, -v16, v113, v47
	v_div_fmas_f32 v16, v16, v45, v113
	v_div_fixup_f32 v16, v16, v4, 1.0
	v_exp_f32_e32 v4, v0
	s_waitcnt vmcnt(0)
; DEVI float sigmoidf_(float x) { return 1.f / (1.f + __expf(-x)); }
; DEVI void gate_tile(const Params& P, int l, int pm, int q, char* smem, int tid) {
;     ...
; #pragma unroll
;     for (int i = 0; i < 4; ++i) {
;       float r = sigmoidf_(rpa[i] + bav[i]);
;       float gi = sigmoidf_(gpa[i] + bxv[i]);
;       float a = __expf(-8.f * log1pf(__expf(-lmv[i])) * r);
;       av[i] = a;
;       uv[i] = sqrtf(fmaxf(1.f - a * a, 0.f)) * gi * xv[i];
;     }
;     *reinterpret_cast<float4*>(au0 + grow * 1024 + col) = make_float4(av[0], av[1], av[2], av[3]);
;     *reinterpret_cast<float4*>(au1 + grow * 1024 + col) = make_float4(uv[0], uv[1], uv[2], uv[3]);
;     *reinterpret_cast<float4*>(Tw + row * 128 + wcc * 64 + c32) = make_float4(av[0], av[1], av[2], av[3]);
;     *reinterpret_cast<float4*>(Tw + row * 128 + wcc * 64 + 32 + c32) = make_float4(uv[0], uv[1], uv[2], uv[3]);
	v_add_f32_e32 v5, 1.0, v5
	v_mul_f32_e32 v1, 0xbfb8aa3b, v1
	v_add_f32_e32 v6, v6, v18
	v_mul_f32_e32 v6, 0xbfb8aa3b, v6
	v_exp_f32_e32 v6, v6
	s_nop 0
	v_add_f32_e32 v6, 1.0, v6
	v_add_f32_e32 v2, v2, v14
	v_mul_f32_e32 v2, 0xbfb8aa3b, v2
	v_add_f32_e32 v7, v7, v19
	v_mul_f32_e32 v7, 0xbfb8aa3b, v7
	v_exp_f32_e32 v7, v7
	v_mov_b32_e32 v0, v240
	v_mul_f32_e32 v0, v16, v0
	v_mul_f32_e32 v0, 0x3fb8aa3b, v0
	v_exp_f32_e32 v0, v0
	v_add_f32_e32 v7, 1.0, v7
	v_add_f32_e32 v3, v3, v15
	v_mul_f32_e32 v3, 0xbfb8aa3b, v3
	v_fma_f32 v8, -v0, v0, 1.0
	v_max_f32_e32 v8, 0, v8
	v_cmp_gt_f32_e32 vcc, s69, v8
	v_mul_f32_e32 v12, 0x4f800000, v8
	s_nop 0
	v_cndmask_b32_e32 v8, v8, v12, vcc
	v_sqrt_f32_e32 v12, v8
	s_nop 0
	v_add_u32_e32 v16, -1, v12
	v_fma_f32 v45, -v16, v12, v8
	v_cmp_ge_f32_e64 s[46:47], 0, v45
	v_add_u32_e32 v45, 1, v12
	s_nop 0
	v_cndmask_b32_e64 v16, v12, v16, s[46:47]
	v_fma_f32 v12, -v45, v12, v8
	v_cmp_lt_f32_e64 s[46:47], 0, v12
	s_nop 1
	v_cndmask_b32_e64 v12, v16, v45, s[46:47]
	v_mul_f32_e32 v16, 0x37800000, v12
	v_cndmask_b32_e32 v12, v12, v16, vcc
	v_cmp_class_f32_e32 vcc, v8, v186
	s_nop 1
	v_cndmask_b32_e32 v8, v12, v8, vcc
	v_div_scale_f32 v12, s[46:47], v5, v5, 1.0
	v_rcp_f32_e32 v16, v12
	s_nop 0
	v_fma_f32 v17, -v12, v16, 1.0
	v_fmac_f32_e32 v16, v17, v16
	v_div_scale_f32 v17, vcc, 1.0, v5, 1.0
	v_mul_f32_e32 v45, v17, v16
	v_fma_f32 v47, -v12, v45, v17
	v_fmac_f32_e32 v45, v47, v16
	v_fma_f32 v12, -v12, v45, v17
	v_div_fmas_f32 v12, v12, v16, v45
	v_div_fixup_f32 v16, v12, v5, 1.0
	v_exp_f32_e32 v5, v1
	s_nop 0
	v_pk_add_f32 v[4:5], v[4:5], 1.0 op_sel_hi:[1,0]
	s_nop 1
	s_nop 1
	s_nop 1
	v_mov_b32_e32 v1, v241
	v_mul_f32_e32 v1, v16, v1
	v_mul_f32_e32 v1, 0x3fb8aa3b, v1
	v_exp_f32_e32 v1, v1
	s_nop 0
	v_fma_f32 v9, -v1, v1, 1.0
	v_max_f32_e32 v9, 0, v9
	v_cmp_gt_f32_e32 vcc, s69, v9
	v_mul_f32_e32 v12, 0x4f800000, v9
	s_nop 0
	v_cndmask_b32_e32 v9, v9, v12, vcc
	v_sqrt_f32_e32 v12, v9
	s_nop 0
	v_add_u32_e32 v13, -1, v12
	v_fma_f32 v16, -v13, v12, v9
	v_cmp_ge_f32_e64 s[46:47], 0, v16
	v_add_u32_e32 v16, 1, v12
	s_nop 0
	v_cndmask_b32_e64 v13, v12, v13, s[46:47]
	v_fma_f32 v12, -v16, v12, v9
	v_cmp_lt_f32_e64 s[46:47], 0, v12
	s_nop 1
	v_cndmask_b32_e64 v12, v13, v16, s[46:47]
	v_mul_f32_e32 v13, 0x37800000, v12
	v_cndmask_b32_e32 v12, v12, v13, vcc
	v_cmp_class_f32_e32 vcc, v9, v186
	s_nop 1
	v_cndmask_b32_e32 v9, v12, v9, vcc
	v_div_scale_f32 v12, s[46:47], v6, v6, 1.0
	v_rcp_f32_e32 v13, v12
	s_nop 0
	v_fma_f32 v16, -v12, v13, 1.0
	v_fmac_f32_e32 v13, v16, v13
	v_div_scale_f32 v16, vcc, 1.0, v6, 1.0
	v_mul_f32_e32 v17, v16, v13
	v_fma_f32 v18, -v12, v17, v16
	v_fmac_f32_e32 v17, v18, v13
	v_fma_f32 v12, -v12, v17, v16
	v_div_fmas_f32 v12, v12, v13, v17
	v_div_fixup_f32 v16, v12, v6, 1.0
	v_exp_f32_e32 v6, v2
	s_nop 0
	s_nop 1
	s_nop 1
	s_nop 1
	v_mov_b32_e32 v2, v242
	v_mul_f32_e32 v2, v16, v2
	v_mul_f32_e32 v2, 0x3fb8aa3b, v2
	v_exp_f32_e32 v2, v2
	s_nop 0
	v_fma_f32 v10, -v2, v2, 1.0
	v_max_f32_e32 v10, 0, v10
	v_cmp_gt_f32_e32 vcc, s69, v10
	v_mul_f32_e32 v12, 0x4f800000, v10
	s_nop 0
	v_cndmask_b32_e32 v10, v10, v12, vcc
	v_sqrt_f32_e32 v12, v10
	s_nop 0
	v_add_u32_e32 v13, -1, v12
	v_fma_f32 v14, -v13, v12, v10
	v_cmp_ge_f32_e64 s[46:47], 0, v14
	v_add_u32_e32 v14, 1, v12
	s_nop 0
	v_cndmask_b32_e64 v13, v12, v13, s[46:47]
	v_fma_f32 v12, -v14, v12, v10
	v_cmp_lt_f32_e64 s[46:47], 0, v12
	s_nop 1
	v_cndmask_b32_e64 v12, v13, v14, s[46:47]
	v_mul_f32_e32 v13, 0x37800000, v12
	v_cndmask_b32_e32 v12, v12, v13, vcc
	v_cmp_class_f32_e32 vcc, v10, v186
	s_nop 1
	v_cndmask_b32_e32 v10, v12, v10, vcc
	v_div_scale_f32 v12, s[46:47], v7, v7, 1.0
	v_rcp_f32_e32 v13, v12
	s_nop 0
	v_fma_f32 v14, -v12, v13, 1.0
	v_fmac_f32_e32 v13, v14, v13
	v_div_scale_f32 v14, vcc, 1.0, v7, 1.0
	v_mul_f32_e32 v16, v14, v13
	v_fma_f32 v17, -v12, v16, v14
	v_fmac_f32_e32 v16, v17, v13
	v_fma_f32 v12, -v12, v16, v14
	v_div_fmas_f32 v12, v12, v13, v16
	v_div_fixup_f32 v14, v12, v7, 1.0
	v_exp_f32_e32 v7, v3
	s_nop 0
	v_pk_add_f32 v[6:7], v[6:7], 1.0 op_sel_hi:[1,0]
	s_nop 1
	s_nop 1
	s_nop 1
	v_mov_b32_e32 v3, v243
	v_mul_f32_e32 v3, v14, v3
	v_mul_f32_e32 v3, 0x3fb8aa3b, v3
	v_exp_f32_e32 v3, v3
	s_nop 0
	v_fma_f32 v11, -v3, v3, 1.0
	v_max_f32_e32 v11, 0, v11
	v_cmp_gt_f32_e32 vcc, s69, v11
	v_mul_f32_e32 v12, 0x4f800000, v11
	s_nop 0
	v_cndmask_b32_e32 v11, v11, v12, vcc
	v_sqrt_f32_e32 v12, v11
	s_nop 0
	v_add_u32_e32 v13, -1, v12
	v_fma_f32 v14, -v13, v12, v11
	v_cmp_ge_f32_e64 s[46:47], 0, v14
	v_add_u32_e32 v14, 1, v12
	s_nop 0
	v_cndmask_b32_e64 v13, v12, v13, s[46:47]
	v_fma_f32 v12, -v14, v12, v11
	v_cmp_lt_f32_e64 s[46:47], 0, v12
	s_nop 1
	v_cndmask_b32_e64 v12, v13, v14, s[46:47]
	v_mul_f32_e32 v13, 0x37800000, v12
	v_cndmask_b32_e32 v12, v12, v13, vcc
	v_cmp_class_f32_e32 vcc, v11, v186
	s_nop 1
	v_cndmask_b32_e32 v11, v12, v11, vcc
	v_lshlrev_b64 v[12:13], 2, v[100:101]
	v_lshl_add_u64 v[14:15], v[56:57], 0, v[12:13]
	global_store_dwordx4 v[14:15], v[0:3], off
	v_div_scale_f32 v14, s[46:47], v5, v5, 1.0
	v_rcp_f32_e32 v15, v14
	v_lshl_add_u64 v[12:13], v[58:59], 0, v[12:13]
	v_fma_f32 v16, -v14, v15, 1.0
	v_fmac_f32_e32 v15, v16, v15
	v_div_scale_f32 v16, vcc, 1.0, v5, 1.0
	v_mul_f32_e32 v17, v16, v15
	v_fma_f32 v18, -v14, v17, v16
	v_fmac_f32_e32 v17, v18, v15
	v_fma_f32 v14, -v14, v17, v16
	v_div_fmas_f32 v14, v14, v15, v17
	v_div_fixup_f32 v5, v14, v5, 1.0
	v_div_scale_f32 v14, s[46:47], v4, v4, 1.0
	v_rcp_f32_e32 v15, v14
	s_nop 0
	v_fma_f32 v16, -v14, v15, 1.0
	v_fmac_f32_e32 v15, v16, v15
	v_div_scale_f32 v16, vcc, 1.0, v4, 1.0
	v_mul_f32_e32 v17, v16, v15
	v_fma_f32 v18, -v14, v17, v16
	v_fmac_f32_e32 v17, v18, v15
; DEVI float sigmoidf_(float x) { return 1.f / (1.f + __expf(-x)); }
; DEVI void gate_tile(const Params& P, int l, int pm, int q, char* smem, int tid) {
;     ...
;   for (int q = 0; q < 8; ++q) {
;     const int id = tid + 256 * q, row = id >> 4, g4 = id & 15;
;     const int cl = g4 * 4, wcc = cl >> 5, c32 = cl & 31;
;     const long grow = (long)pm * 128 + row;
;     const int col = nb * 128 + hb * 64 + cl;
;     float4 rp = *reinterpret_cast<const float4*>(T + row * 128 + wcc * 64 + c32);
;     float4 gp = *reinterpret_cast<const float4*>(T + row * 128 + wcc * 64 + 32 + c32);
;     float xv[4], bav[4], bxv[4], lmv[4];
;     load4bf(cb + grow * 1024 + col, xv);
;     ld4f(ba + col, bav); ld4f(bx + col, bxv); ld4f(lam + col, lmv);
;     const float rpa[4] = {rp.x, rp.y, rp.z, rp.w}, gpa[4] = {gp.x, gp.y, gp.z, gp.w};
;     float av[4], uv[4];
; #pragma unroll
;     for (int i = 0; i < 4; ++i) {
;       float r = sigmoidf_(rpa[i] + bav[i]);
;       float gi = sigmoidf_(gpa[i] + bxv[i]);
;       float a = __expf(-8.f * log1pf(__expf(-lmv[i])) * r);
;       av[i] = a;
;       uv[i] = sqrtf(fmaxf(1.f - a * a, 0.f)) * gi * xv[i];
;     }
;     *reinterpret_cast<float4*>(au0 + grow * 1024 + col) = make_float4(av[0], av[1], av[2], av[3]);
;     *reinterpret_cast<float4*>(au1 + grow * 1024 + col) = make_float4(uv[0], uv[1], uv[2], uv[3]);
;     *reinterpret_cast<float4*>(Tw + row * 128 + wcc * 64 + c32) = make_float4(av[0], av[1], av[2], av[3]);
;     *reinterpret_cast<float4*>(Tw + row * 128 + wcc * 64 + 32 + c32) = make_float4(uv[0], uv[1], uv[2], uv[3]);
	v_fma_f32 v14, -v14, v17, v16
	v_div_fmas_f32 v14, v14, v15, v17
	v_div_fixup_f32 v4, v14, v4, 1.0
	v_pk_mul_f32 v[4:5], v[4:5], v[8:9]
	v_div_scale_f32 v8, s[46:47], v7, v7, 1.0
	v_rcp_f32_e32 v9, v8
	v_pk_mul_f32 v[4:5], v[4:5], v[62:63]
	v_fma_f32 v14, -v8, v9, 1.0
	v_fmac_f32_e32 v9, v14, v9
	v_div_scale_f32 v14, vcc, 1.0, v7, 1.0
	v_mul_f32_e32 v15, v14, v9
	v_fma_f32 v16, -v8, v15, v14
	v_fmac_f32_e32 v15, v16, v9
	v_fma_f32 v8, -v8, v15, v14
	v_div_fmas_f32 v8, v8, v9, v15
	v_div_fixup_f32 v7, v8, v7, 1.0
	v_div_scale_f32 v8, s[46:47], v6, v6, 1.0
	v_rcp_f32_e32 v9, v8
	s_nop 0
	v_fma_f32 v14, -v8, v9, 1.0
	v_fmac_f32_e32 v9, v14, v9
	v_div_scale_f32 v14, vcc, 1.0, v6, 1.0
	v_mul_f32_e32 v15, v14, v9
	v_fma_f32 v16, -v8, v15, v14
	v_fmac_f32_e32 v15, v16, v9
	v_fma_f32 v8, -v8, v15, v14
	v_div_fmas_f32 v8, v8, v9, v15
	v_div_fixup_f32 v6, v8, v6, 1.0
	v_pk_mul_f32 v[6:7], v[6:7], v[10:11]
	s_nop 0
	v_pk_mul_f32 v[6:7], v[6:7], v[60:61]
	global_store_dwordx4 v[12:13], v[4:7], off
	ds_write_b128 v43, v[0:3]
	ds_write_b128 v43, v[4:7] offset:128
	v_add_u32_e32 v0, 0x100, v41
	v_ashrrev_i32_e32 v4, 4, v0
	v_ashrrev_i32_e32 v5, 31, v4
	v_lshl_or_b32 v43, v4, 9, v112
	v_lshlrev_b64 v[4:5], 10, v[4:5]
	v_lshl_add_u64 v[100:101], v[4:5], 0, s[54:55]
	v_lshl_add_u64 v[4:5], v[100:101], 1, v[48:49]
	ds_read_b128 v[12:15], v43
	ds_read_b128 v[0:3], v43 offset:128
	global_load_dwordx2 v[4:5], v[4:5], off
	s_waitcnt vmcnt(0)
	v_lshlrev_b32_e32 v62, 16, v4
	v_and_b32_e32 v63, 0xffff0000, v4
	v_lshlrev_b32_e32 v60, 16, v5
	v_and_b32_e32 v61, 0xffff0000, v5
	global_load_dwordx4 v[16:19], v[50:51], off
	global_load_dwordx4 v[8:11], v[52:53], off
	global_load_dwordx4 v[4:7], v[54:55], off
	s_waitcnt vmcnt(2) lgkmcnt(1)
	v_add_f32_e32 v12, v12, v16
	v_mul_f32_e32 v12, 0xbfb8aa3b, v12
	v_exp_f32_e32 v12, v12
	s_waitcnt vmcnt(1) lgkmcnt(0)
	v_add_f32_e32 v0, v0, v8
	v_mul_f32_e32 v0, 0xbfb8aa3b, v0
	v_exp_f32_e32 v8, v0
	v_add_f32_e32 v12, 1.0, v12
	v_div_scale_f32 v16, s[46:47], v12, v12, 1.0
	v_rcp_f32_e32 v45, v16
	s_waitcnt vmcnt(0)
	v_add_f32_e32 v1, v1, v9
	v_fma_f32 v47, -v16, v45, 1.0
	v_fmac_f32_e32 v45, v47, v45
	v_div_scale_f32 v47, vcc, 1.0, v12, 1.0
	v_mul_f32_e32 v113, v47, v45
	v_fma_f32 v114, -v16, v113, v47
	v_fmac_f32_e32 v113, v114, v45
	v_fma_f32 v16, -v16, v113, v47
	v_div_fmas_f32 v16, v16, v45, v113
	v_div_fixup_f32 v12, v16, v12, 1.0
	v_mul_f32_e32 v1, 0xbfb8aa3b, v1
	v_exp_f32_e32 v9, v1
	v_add_f32_e32 v2, v2, v10
	v_mul_f32_e32 v2, 0xbfb8aa3b, v2
	v_exp_f32_e32 v10, v2
	v_mov_b32_e32 v0, v240
	v_mul_f32_e32 v0, v12, v0
	v_mul_f32_e32 v0, 0x3fb8aa3b, v0
	v_exp_f32_e32 v0, v0
	v_add_f32_e32 v3, v3, v11
	v_fma_f32 v4, -v0, v0, 1.0
	v_max_f32_e32 v4, 0, v4
	v_cmp_gt_f32_e32 vcc, s69, v4
	v_mul_f32_e32 v12, 0x4f800000, v4
	s_nop 0
	v_cndmask_b32_e32 v4, v4, v12, vcc
	v_sqrt_f32_e32 v12, v4
	v_mul_f32_e32 v3, 0xbfb8aa3b, v3
	v_exp_f32_e32 v11, v3
	v_add_u32_e32 v16, -1, v12
	v_fma_f32 v45, -v16, v12, v4
	v_cmp_ge_f32_e64 s[46:47], 0, v45
	v_add_u32_e32 v45, 1, v12
	s_nop 0
	v_cndmask_b32_e64 v16, v12, v16, s[46:47]
	v_fma_f32 v12, -v45, v12, v4
	v_cmp_lt_f32_e64 s[46:47], 0, v12
	v_pk_add_f32 v[8:9], v[8:9], 1.0 op_sel_hi:[1,0]
	s_nop 0
	v_cndmask_b32_e64 v12, v16, v45, s[46:47]
	v_mul_f32_e32 v16, 0x37800000, v12
	v_cndmask_b32_e32 v12, v12, v16, vcc
	v_cmp_class_f32_e32 vcc, v4, v186
	s_nop 1
	v_cndmask_b32_e32 v4, v12, v4, vcc
	v_add_f32_e32 v12, v13, v17
	v_mul_f32_e32 v12, 0xbfb8aa3b, v12
	v_exp_f32_e32 v12, v12
	s_nop 0
	v_add_f32_e32 v12, 1.0, v12
	v_div_scale_f32 v13, s[46:47], v12, v12, 1.0
	v_rcp_f32_e32 v16, v13
	s_nop 0
	v_fma_f32 v17, -v13, v16, 1.0
	v_fmac_f32_e32 v16, v17, v16
	v_div_scale_f32 v17, vcc, 1.0, v12, 1.0
	v_mul_f32_e32 v45, v17, v16
	v_fma_f32 v47, -v13, v45, v17
	v_fmac_f32_e32 v45, v47, v16
	v_fma_f32 v13, -v13, v45, v17
	v_div_fmas_f32 v13, v13, v16, v45
	v_div_fixup_f32 v16, v13, v12, 1.0
	s_nop 1
	s_nop 1
	s_nop 1
	v_mov_b32_e32 v1, v241
	v_mul_f32_e32 v1, v16, v1
	v_mul_f32_e32 v1, 0x3fb8aa3b, v1
	v_exp_f32_e32 v1, v1
	s_nop 0
	v_fma_f32 v5, -v1, v1, 1.0
	v_max_f32_e32 v5, 0, v5
	v_cmp_gt_f32_e32 vcc, s69, v5
	v_mul_f32_e32 v12, 0x4f800000, v5
	s_nop 0
	v_cndmask_b32_e32 v5, v5, v12, vcc
	v_sqrt_f32_e32 v12, v5
	s_nop 0
	v_add_u32_e32 v13, -1, v12
	v_fma_f32 v16, -v13, v12, v5
	v_cmp_ge_f32_e64 s[46:47], 0, v16
	v_add_u32_e32 v16, 1, v12
	s_nop 0
	v_cndmask_b32_e64 v13, v12, v13, s[46:47]
	v_fma_f32 v12, -v16, v12, v5
	v_cmp_lt_f32_e64 s[46:47], 0, v12
	s_nop 1
	v_cndmask_b32_e64 v12, v13, v16, s[46:47]
	v_mul_f32_e32 v13, 0x37800000, v12
	v_cndmask_b32_e32 v12, v12, v13, vcc
	v_cmp_class_f32_e32 vcc, v5, v186
	s_nop 1
	v_cndmask_b32_e32 v5, v12, v5, vcc
	v_add_f32_e32 v12, v14, v18
	v_mul_f32_e32 v12, 0xbfb8aa3b, v12
	v_exp_f32_e32 v12, v12
	s_nop 0
	v_add_f32_e32 v12, 1.0, v12
	v_div_scale_f32 v13, s[46:47], v12, v12, 1.0
	v_rcp_f32_e32 v14, v13
	s_nop 0
	v_fma_f32 v16, -v13, v14, 1.0
	v_fmac_f32_e32 v14, v16, v14
	v_div_scale_f32 v16, vcc, 1.0, v12, 1.0
	v_mul_f32_e32 v17, v16, v14
	v_fma_f32 v18, -v13, v17, v16
	v_fmac_f32_e32 v17, v18, v14
	v_fma_f32 v13, -v13, v17, v16
	v_div_fmas_f32 v13, v13, v14, v17
	v_div_fixup_f32 v14, v13, v12, 1.0
	s_nop 1
	s_nop 1
	s_nop 1
	v_mov_b32_e32 v2, v242
	v_mul_f32_e32 v2, v14, v2
	v_mul_f32_e32 v2, 0x3fb8aa3b, v2
	v_exp_f32_e32 v2, v2
	s_nop 0
	v_fma_f32 v6, -v2, v2, 1.0
	v_max_f32_e32 v6, 0, v6
	v_cmp_gt_f32_e32 vcc, s69, v6
	v_mul_f32_e32 v12, 0x4f800000, v6
	s_nop 0
	v_cndmask_b32_e32 v6, v6, v12, vcc
	v_sqrt_f32_e32 v12, v6
	s_nop 0
	v_add_u32_e32 v13, -1, v12
	v_fma_f32 v14, -v13, v12, v6
	v_cmp_ge_f32_e64 s[46:47], 0, v14
	v_add_u32_e32 v14, 1, v12
; DEVI float sigmoidf_(float x) { return 1.f / (1.f + __expf(-x)); }
; DEVI void gate_tile(const Params& P, int l, int pm, int q, char* smem, int tid) {
;     ...
;   for (int q = 0; q < 8; ++q) {
;     const int id = tid + 256 * q, row = id >> 4, g4 = id & 15;
;     const int cl = g4 * 4, wcc = cl >> 5, c32 = cl & 31;
;     const long grow = (long)pm * 128 + row;
;     const int col = nb * 128 + hb * 64 + cl;
;     float4 rp = *reinterpret_cast<const float4*>(T + row * 128 + wcc * 64 + c32);
;     float4 gp = *reinterpret_cast<const float4*>(T + row * 128 + wcc * 64 + 32 + c32);
;     float xv[4], bav[4], bxv[4], lmv[4];
;     load4bf(cb + grow * 1024 + col, xv);
;     ld4f(ba + col, bav); ld4f(bx + col, bxv); ld4f(lam + col, lmv);
;     const float rpa[4] = {rp.x, rp.y, rp.z, rp.w}, gpa[4] = {gp.x, gp.y, gp.z, gp.w};
;     float av[4], uv[4];
; #pragma unroll
;     for (int i = 0; i < 4; ++i) {
;       float r = sigmoidf_(rpa[i] + bav[i]);
;       float gi = sigmoidf_(gpa[i] + bxv[i]);
;       float a = __expf(-8.f * log1pf(__expf(-lmv[i])) * r);
;       av[i] = a;
;       uv[i] = sqrtf(fmaxf(1.f - a * a, 0.f)) * gi * xv[i];
;     }
;     *reinterpret_cast<float4*>(au0 + grow * 1024 + col) = make_float4(av[0], av[1], av[2], av[3]);
;     *reinterpret_cast<float4*>(au1 + grow * 1024 + col) = make_float4(uv[0], uv[1], uv[2], uv[3]);
;     *reinterpret_cast<float4*>(Tw + row * 128 + wcc * 64 + c32) = make_float4(av[0], av[1], av[2], av[3]);
;     *reinterpret_cast<float4*>(Tw + row * 128 + wcc * 64 + 32 + c32) = make_float4(uv[0], uv[1], uv[2], uv[3]);
	s_nop 0
	v_cndmask_b32_e64 v13, v12, v13, s[46:47]
	v_fma_f32 v12, -v14, v12, v6
	v_cmp_lt_f32_e64 s[46:47], 0, v12
	s_nop 1
	v_cndmask_b32_e64 v12, v13, v14, s[46:47]
	v_mul_f32_e32 v13, 0x37800000, v12
	v_cndmask_b32_e32 v12, v12, v13, vcc
	v_cmp_class_f32_e32 vcc, v6, v186
	s_nop 1
	v_cndmask_b32_e32 v6, v12, v6, vcc
	v_add_f32_e32 v12, v15, v19
	v_mul_f32_e32 v12, 0xbfb8aa3b, v12
	v_exp_f32_e32 v12, v12
	s_nop 0
	v_add_f32_e32 v12, 1.0, v12
	v_div_scale_f32 v13, s[46:47], v12, v12, 1.0
	v_rcp_f32_e32 v14, v13
	s_nop 0
	v_fma_f32 v15, -v13, v14, 1.0
	v_fmac_f32_e32 v14, v15, v14
	v_div_scale_f32 v15, vcc, 1.0, v12, 1.0
	v_mul_f32_e32 v16, v15, v14
	v_fma_f32 v17, -v13, v16, v15
	v_fmac_f32_e32 v16, v17, v14
	v_fma_f32 v13, -v13, v16, v15
	v_div_fmas_f32 v13, v13, v14, v16
	v_div_fixup_f32 v14, v13, v12, 1.0
	s_nop 1
	s_nop 1
	s_nop 1
	v_mov_b32_e32 v3, v243
	v_mul_f32_e32 v3, v14, v3
	v_mul_f32_e32 v3, 0x3fb8aa3b, v3
	v_exp_f32_e32 v3, v3
	s_nop 0
	v_fma_f32 v7, -v3, v3, 1.0
	v_max_f32_e32 v7, 0, v7
	v_cmp_gt_f32_e32 vcc, s69, v7
	v_mul_f32_e32 v12, 0x4f800000, v7
	s_nop 0
	v_cndmask_b32_e32 v7, v7, v12, vcc
	v_sqrt_f32_e32 v12, v7
	s_nop 0
	v_add_u32_e32 v13, -1, v12
	v_fma_f32 v14, -v13, v12, v7
	v_cmp_ge_f32_e64 s[46:47], 0, v14
	v_add_u32_e32 v14, 1, v12
	s_nop 0
	v_cndmask_b32_e64 v13, v12, v13, s[46:47]
	v_fma_f32 v12, -v14, v12, v7
	v_cmp_lt_f32_e64 s[46:47], 0, v12
	s_nop 1
	v_cndmask_b32_e64 v12, v13, v14, s[46:47]
	v_mul_f32_e32 v13, 0x37800000, v12
	v_cndmask_b32_e32 v12, v12, v13, vcc
	v_cmp_class_f32_e32 vcc, v7, v186
	s_nop 1
	v_cndmask_b32_e32 v7, v12, v7, vcc
	v_lshlrev_b64 v[12:13], 2, v[100:101]
	v_lshl_add_u64 v[14:15], v[56:57], 0, v[12:13]
	global_store_dwordx4 v[14:15], v[0:3], off
	v_div_scale_f32 v14, s[46:47], v9, v9, 1.0
	v_rcp_f32_e32 v15, v14
	v_lshl_add_u64 v[12:13], v[58:59], 0, v[12:13]
	v_fma_f32 v16, -v14, v15, 1.0
	v_fmac_f32_e32 v15, v16, v15
	v_div_scale_f32 v16, vcc, 1.0, v9, 1.0
	v_mul_f32_e32 v17, v16, v15
	v_fma_f32 v18, -v14, v17, v16
	v_fmac_f32_e32 v17, v18, v15
	v_fma_f32 v14, -v14, v17, v16
	v_div_fmas_f32 v14, v14, v15, v17
	v_div_fixup_f32 v9, v14, v9, 1.0
	v_div_scale_f32 v14, s[46:47], v8, v8, 1.0
	v_rcp_f32_e32 v15, v14
	s_nop 0
	v_fma_f32 v16, -v14, v15, 1.0
	v_fmac_f32_e32 v15, v16, v15
	v_div_scale_f32 v16, vcc, 1.0, v8, 1.0
	v_mul_f32_e32 v17, v16, v15
	v_fma_f32 v18, -v14, v17, v16
	v_fmac_f32_e32 v17, v18, v15
	v_fma_f32 v14, -v14, v17, v16
	v_div_fmas_f32 v14, v14, v15, v17
	v_div_fixup_f32 v8, v14, v8, 1.0
	v_pk_mul_f32 v[4:5], v[8:9], v[4:5]
	v_pk_add_f32 v[8:9], v[10:11], 1.0 op_sel_hi:[1,0]
	v_pk_mul_f32 v[4:5], v[4:5], v[62:63]
	v_div_scale_f32 v10, s[46:47], v9, v9, 1.0
	v_rcp_f32_e32 v11, v10
	s_nop 0
	v_fma_f32 v14, -v10, v11, 1.0
	v_fmac_f32_e32 v11, v14, v11
	v_div_scale_f32 v14, vcc, 1.0, v9, 1.0
	v_mul_f32_e32 v15, v14, v11
	v_fma_f32 v16, -v10, v15, v14
	v_fmac_f32_e32 v15, v16, v11
	v_fma_f32 v10, -v10, v15, v14
	v_div_fmas_f32 v10, v10, v11, v15
	v_div_fixup_f32 v9, v10, v9, 1.0
	v_div_scale_f32 v10, s[46:47], v8, v8, 1.0
	v_rcp_f32_e32 v11, v10
	s_nop 0
	v_fma_f32 v14, -v10, v11, 1.0
	v_fmac_f32_e32 v11, v14, v11
	v_div_scale_f32 v14, vcc, 1.0, v8, 1.0
	v_mul_f32_e32 v15, v14, v11
	v_fma_f32 v16, -v10, v15, v14
	v_fmac_f32_e32 v15, v16, v11
	v_fma_f32 v10, -v10, v15, v14
	v_div_fmas_f32 v10, v10, v11, v15
	v_div_fixup_f32 v8, v10, v8, 1.0
	v_pk_mul_f32 v[6:7], v[8:9], v[6:7]
	s_nop 0
	v_pk_mul_f32 v[6:7], v[6:7], v[60:61]
	global_store_dwordx4 v[12:13], v[4:7], off
	ds_write_b128 v43, v[0:3]
	ds_write_b128 v43, v[4:7] offset:128
	v_add_u32_e32 v0, 0x200, v41
	v_ashrrev_i32_e32 v4, 4, v0
	v_ashrrev_i32_e32 v5, 31, v4
	v_lshl_or_b32 v43, v4, 9, v112
	v_lshlrev_b64 v[4:5], 10, v[4:5]
	v_lshl_add_u64 v[100:101], v[4:5], 0, s[54:55]
	v_lshl_add_u64 v[4:5], v[100:101], 1, v[48:49]
	ds_read_b128 v[12:15], v43
	ds_read_b128 v[0:3], v43 offset:128
	global_load_dwordx2 v[4:5], v[4:5], off
	s_waitcnt vmcnt(0)
	v_lshlrev_b32_e32 v62, 16, v4
	v_and_b32_e32 v63, 0xffff0000, v4
	v_lshlrev_b32_e32 v60, 16, v5
	v_and_b32_e32 v61, 0xffff0000, v5
	global_load_dwordx4 v[16:19], v[50:51], off
	global_load_dwordx4 v[8:11], v[52:53], off
	global_load_dwordx4 v[4:7], v[54:55], off
	s_waitcnt vmcnt(2) lgkmcnt(1)
	v_add_f32_e32 v12, v12, v16
	v_mul_f32_e32 v12, 0xbfb8aa3b, v12
	v_exp_f32_e32 v12, v12
	s_waitcnt vmcnt(1) lgkmcnt(0)
	v_add_f32_e32 v0, v0, v8
	v_mul_f32_e32 v0, 0xbfb8aa3b, v0
	v_exp_f32_e32 v8, v0
	v_add_f32_e32 v12, 1.0, v12
	v_div_scale_f32 v16, s[46:47], v12, v12, 1.0
	v_rcp_f32_e32 v45, v16
	s_waitcnt vmcnt(0)
; DEVI float sigmoidf_(float x) { return 1.f / (1.f + __expf(-x)); }
; DEVI void gate_tile(const Params& P, int l, int pm, int q, char* smem, int tid) {
;     ...
;   for (int q = 0; q < 8; ++q) {
;     const int id = tid + 256 * q, row = id >> 4, g4 = id & 15;
;     const int cl = g4 * 4, wcc = cl >> 5, c32 = cl & 31;
;     const long grow = (long)pm * 128 + row;
;     const int col = nb * 128 + hb * 64 + cl;
;     float4 rp = *reinterpret_cast<const float4*>(T + row * 128 + wcc * 64 + c32);
;     float4 gp = *reinterpret_cast<const float4*>(T + row * 128 + wcc * 64 + 32 + c32);
;     float xv[4], bav[4], bxv[4], lmv[4];
;     load4bf(cb + grow * 1024 + col, xv);
;     ld4f(ba + col, bav); ld4f(bx + col, bxv); ld4f(lam + col, lmv);
;     const float rpa[4] = {rp.x, rp.y, rp.z, rp.w}, gpa[4] = {gp.x, gp.y, gp.z, gp.w};
;     float av[4], uv[4];
; #pragma unroll
;     for (int i = 0; i < 4; ++i) {
;       float r = sigmoidf_(rpa[i] + bav[i]);
;       float gi = sigmoidf_(gpa[i] + bxv[i]);
;       float a = __expf(-8.f * log1pf(__expf(-lmv[i])) * r);
;       av[i] = a;
;       uv[i] = sqrtf(fmaxf(1.f - a * a, 0.f)) * gi * xv[i];
;     }
;     *reinterpret_cast<float4*>(au0 + grow * 1024 + col) = make_float4(av[0], av[1], av[2], av[3]);
;     *reinterpret_cast<float4*>(au1 + grow * 1024 + col) = make_float4(uv[0], uv[1], uv[2], uv[3]);
;     *reinterpret_cast<float4*>(Tw + row * 128 + wcc * 64 + c32) = make_float4(av[0], av[1], av[2], av[3]);
;     *reinterpret_cast<float4*>(Tw + row * 128 + wcc * 64 + 32 + c32) = make_float4(uv[0], uv[1], uv[2], uv[3]);
	v_add_f32_e32 v1, v1, v9
	v_fma_f32 v47, -v16, v45, 1.0
	v_fmac_f32_e32 v45, v47, v45
	v_div_scale_f32 v47, vcc, 1.0, v12, 1.0
	v_mul_f32_e32 v113, v47, v45
	v_fma_f32 v114, -v16, v113, v47
	v_fmac_f32_e32 v113, v114, v45
	v_fma_f32 v16, -v16, v113, v47
	v_div_fmas_f32 v16, v16, v45, v113
	v_div_fixup_f32 v12, v16, v12, 1.0
	v_mul_f32_e32 v1, 0xbfb8aa3b, v1
	v_exp_f32_e32 v9, v1
	v_add_f32_e32 v2, v2, v10
	v_mul_f32_e32 v2, 0xbfb8aa3b, v2
	v_exp_f32_e32 v10, v2
	v_mov_b32_e32 v0, v240
	v_mul_f32_e32 v0, v12, v0
	v_mul_f32_e32 v0, 0x3fb8aa3b, v0
	v_exp_f32_e32 v0, v0
	v_add_f32_e32 v3, v3, v11
	v_fma_f32 v4, -v0, v0, 1.0
	v_max_f32_e32 v4, 0, v4
	v_cmp_gt_f32_e32 vcc, s69, v4
	v_mul_f32_e32 v12, 0x4f800000, v4
	s_nop 0
	v_cndmask_b32_e32 v4, v4, v12, vcc
	v_sqrt_f32_e32 v12, v4
	v_mul_f32_e32 v3, 0xbfb8aa3b, v3
	v_exp_f32_e32 v11, v3
	v_add_u32_e32 v16, -1, v12
	v_fma_f32 v45, -v16, v12, v4
	v_cmp_ge_f32_e64 s[46:47], 0, v45
	v_add_u32_e32 v45, 1, v12
	s_nop 0
	v_cndmask_b32_e64 v16, v12, v16, s[46:47]
	v_fma_f32 v12, -v45, v12, v4
	v_cmp_lt_f32_e64 s[46:47], 0, v12
	v_pk_add_f32 v[8:9], v[8:9], 1.0 op_sel_hi:[1,0]
	s_nop 0
	v_cndmask_b32_e64 v12, v16, v45, s[46:47]
	v_mul_f32_e32 v16, 0x37800000, v12
	v_cndmask_b32_e32 v12, v12, v16, vcc
	v_cmp_class_f32_e32 vcc, v4, v186
	s_nop 1
	v_cndmask_b32_e32 v4, v12, v4, vcc
	v_add_f32_e32 v12, v13, v17
	v_mul_f32_e32 v12, 0xbfb8aa3b, v12
	v_exp_f32_e32 v12, v12
	s_nop 0
	v_add_f32_e32 v12, 1.0, v12
	v_div_scale_f32 v13, s[46:47], v12, v12, 1.0
	v_rcp_f32_e32 v16, v13
	s_nop 0
	v_fma_f32 v17, -v13, v16, 1.0
	v_fmac_f32_e32 v16, v17, v16
	v_div_scale_f32 v17, vcc, 1.0, v12, 1.0
	v_mul_f32_e32 v45, v17, v16
	v_fma_f32 v47, -v13, v45, v17
	v_fmac_f32_e32 v45, v47, v16
	v_fma_f32 v13, -v13, v45, v17
	v_div_fmas_f32 v13, v13, v16, v45
	v_div_fixup_f32 v16, v13, v12, 1.0
	s_nop 1
	s_nop 1
	s_nop 1
	v_mov_b32_e32 v1, v241
	v_mul_f32_e32 v1, v16, v1
	v_mul_f32_e32 v1, 0x3fb8aa3b, v1
	v_exp_f32_e32 v1, v1
	s_nop 0
	v_fma_f32 v5, -v1, v1, 1.0
	v_max_f32_e32 v5, 0, v5
	v_cmp_gt_f32_e32 vcc, s69, v5
	v_mul_f32_e32 v12, 0x4f800000, v5
	s_nop 0
	v_cndmask_b32_e32 v5, v5, v12, vcc
	v_sqrt_f32_e32 v12, v5
	s_nop 0
	v_add_u32_e32 v13, -1, v12
	v_fma_f32 v16, -v13, v12, v5
	v_cmp_ge_f32_e64 s[46:47], 0, v16
	v_add_u32_e32 v16, 1, v12
	s_nop 0
	v_cndmask_b32_e64 v13, v12, v13, s[46:47]
	v_fma_f32 v12, -v16, v12, v5
	v_cmp_lt_f32_e64 s[46:47], 0, v12
	s_nop 1
	v_cndmask_b32_e64 v12, v13, v16, s[46:47]
	v_mul_f32_e32 v13, 0x37800000, v12
	v_cndmask_b32_e32 v12, v12, v13, vcc
	v_cmp_class_f32_e32 vcc, v5, v186
	s_nop 1
	v_cndmask_b32_e32 v5, v12, v5, vcc
	v_add_f32_e32 v12, v14, v18
	v_mul_f32_e32 v12, 0xbfb8aa3b, v12
	v_exp_f32_e32 v12, v12
	s_nop 0
	v_add_f32_e32 v12, 1.0, v12
	v_div_scale_f32 v13, s[46:47], v12, v12, 1.0
	v_rcp_f32_e32 v14, v13
	s_nop 0
	v_fma_f32 v16, -v13, v14, 1.0
	v_fmac_f32_e32 v14, v16, v14
	v_div_scale_f32 v16, vcc, 1.0, v12, 1.0
	v_mul_f32_e32 v17, v16, v14
	v_fma_f32 v18, -v13, v17, v16
	v_fmac_f32_e32 v17, v18, v14
	v_fma_f32 v13, -v13, v17, v16
	v_div_fmas_f32 v13, v13, v14, v17
	v_div_fixup_f32 v14, v13, v12, 1.0
	s_nop 1
	s_nop 1
	s_nop 1
	v_mov_b32_e32 v2, v242
	v_mul_f32_e32 v2, v14, v2
	v_mul_f32_e32 v2, 0x3fb8aa3b, v2
	v_exp_f32_e32 v2, v2
	s_nop 0
	v_fma_f32 v6, -v2, v2, 1.0
	v_max_f32_e32 v6, 0, v6
	v_cmp_gt_f32_e32 vcc, s69, v6
	v_mul_f32_e32 v12, 0x4f800000, v6
	s_nop 0
	v_cndmask_b32_e32 v6, v6, v12, vcc
	v_sqrt_f32_e32 v12, v6
	s_nop 0
	v_add_u32_e32 v13, -1, v12
	v_fma_f32 v14, -v13, v12, v6
	v_cmp_ge_f32_e64 s[46:47], 0, v14
	v_add_u32_e32 v14, 1, v12
	s_nop 0
	v_cndmask_b32_e64 v13, v12, v13, s[46:47]
	v_fma_f32 v12, -v14, v12, v6
	v_cmp_lt_f32_e64 s[46:47], 0, v12
	s_nop 1
	v_cndmask_b32_e64 v12, v13, v14, s[46:47]
	v_mul_f32_e32 v13, 0x37800000, v12
	v_cndmask_b32_e32 v12, v12, v13, vcc
	v_cmp_class_f32_e32 vcc, v6, v186
	s_nop 1
	v_cndmask_b32_e32 v6, v12, v6, vcc
	v_add_f32_e32 v12, v15, v19
	v_mul_f32_e32 v12, 0xbfb8aa3b, v12
	v_exp_f32_e32 v12, v12
	s_nop 0
	v_add_f32_e32 v12, 1.0, v12
	v_div_scale_f32 v13, s[46:47], v12, v12, 1.0
	v_rcp_f32_e32 v14, v13
	s_nop 0
	v_fma_f32 v15, -v13, v14, 1.0
	v_fmac_f32_e32 v14, v15, v14
	v_div_scale_f32 v15, vcc, 1.0, v12, 1.0
	v_mul_f32_e32 v16, v15, v14
	v_fma_f32 v17, -v13, v16, v15
	v_fmac_f32_e32 v16, v17, v14
	v_fma_f32 v13, -v13, v16, v15
	v_div_fmas_f32 v13, v13, v14, v16
	v_div_fixup_f32 v14, v13, v12, 1.0
	s_nop 1
	s_nop 1
	s_nop 1
	v_mov_b32_e32 v3, v243
	v_mul_f32_e32 v3, v14, v3
	v_mul_f32_e32 v3, 0x3fb8aa3b, v3
	v_exp_f32_e32 v3, v3
	s_nop 0
	v_fma_f32 v7, -v3, v3, 1.0
	v_max_f32_e32 v7, 0, v7
	v_cmp_gt_f32_e32 vcc, s69, v7
	v_mul_f32_e32 v12, 0x4f800000, v7
	s_nop 0
	v_cndmask_b32_e32 v7, v7, v12, vcc
	v_sqrt_f32_e32 v12, v7
	s_nop 0
	v_add_u32_e32 v13, -1, v12
	v_fma_f32 v14, -v13, v12, v7
	v_cmp_ge_f32_e64 s[46:47], 0, v14
	v_add_u32_e32 v14, 1, v12
	s_nop 0
	v_cndmask_b32_e64 v13, v12, v13, s[46:47]
	v_fma_f32 v12, -v14, v12, v7
	v_cmp_lt_f32_e64 s[46:47], 0, v12
	s_nop 1
	v_cndmask_b32_e64 v12, v13, v14, s[46:47]
	v_mul_f32_e32 v13, 0x37800000, v12
	v_cndmask_b32_e32 v12, v12, v13, vcc
	v_cmp_class_f32_e32 vcc, v7, v186
	s_nop 1
	v_cndmask_b32_e32 v7, v12, v7, vcc
	v_lshlrev_b64 v[12:13], 2, v[100:101]
	v_lshl_add_u64 v[14:15], v[56:57], 0, v[12:13]
	global_store_dwordx4 v[14:15], v[0:3], off
	v_div_scale_f32 v14, s[46:47], v9, v9, 1.0
	v_rcp_f32_e32 v15, v14
	v_lshl_add_u64 v[12:13], v[58:59], 0, v[12:13]
	v_fma_f32 v16, -v14, v15, 1.0
	v_fmac_f32_e32 v15, v16, v15
	v_div_scale_f32 v16, vcc, 1.0, v9, 1.0
	v_mul_f32_e32 v17, v16, v15
	v_fma_f32 v18, -v14, v17, v16
	v_fmac_f32_e32 v17, v18, v15
; DEVI float sigmoidf_(float x) { return 1.f / (1.f + __expf(-x)); }
; DEVI void gate_tile(const Params& P, int l, int pm, int q, char* smem, int tid) {
;     ...
;   for (int q = 0; q < 8; ++q) {
;     const int id = tid + 256 * q, row = id >> 4, g4 = id & 15;
;     const int cl = g4 * 4, wcc = cl >> 5, c32 = cl & 31;
;     const long grow = (long)pm * 128 + row;
;     const int col = nb * 128 + hb * 64 + cl;
;     float4 rp = *reinterpret_cast<const float4*>(T + row * 128 + wcc * 64 + c32);
;     float4 gp = *reinterpret_cast<const float4*>(T + row * 128 + wcc * 64 + 32 + c32);
;     float xv[4], bav[4], bxv[4], lmv[4];
;     load4bf(cb + grow * 1024 + col, xv);
;     ld4f(ba + col, bav); ld4f(bx + col, bxv); ld4f(lam + col, lmv);
;     const float rpa[4] = {rp.x, rp.y, rp.z, rp.w}, gpa[4] = {gp.x, gp.y, gp.z, gp.w};
;     float av[4], uv[4];
; #pragma unroll
;     for (int i = 0; i < 4; ++i) {
;       float r = sigmoidf_(rpa[i] + bav[i]);
;       float gi = sigmoidf_(gpa[i] + bxv[i]);
;       float a = __expf(-8.f * log1pf(__expf(-lmv[i])) * r);
;       av[i] = a;
;       uv[i] = sqrtf(fmaxf(1.f - a * a, 0.f)) * gi * xv[i];
;     }
;     *reinterpret_cast<float4*>(au0 + grow * 1024 + col) = make_float4(av[0], av[1], av[2], av[3]);
;     *reinterpret_cast<float4*>(au1 + grow * 1024 + col) = make_float4(uv[0], uv[1], uv[2], uv[3]);
;     *reinterpret_cast<float4*>(Tw + row * 128 + wcc * 64 + c32) = make_float4(av[0], av[1], av[2], av[3]);
;     *reinterpret_cast<float4*>(Tw + row * 128 + wcc * 64 + 32 + c32) = make_float4(uv[0], uv[1], uv[2], uv[3]);
	v_fma_f32 v14, -v14, v17, v16
	v_div_fmas_f32 v14, v14, v15, v17
	v_div_fixup_f32 v9, v14, v9, 1.0
	v_div_scale_f32 v14, s[46:47], v8, v8, 1.0
	v_rcp_f32_e32 v15, v14
	s_nop 0
	v_fma_f32 v16, -v14, v15, 1.0
	v_fmac_f32_e32 v15, v16, v15
	v_div_scale_f32 v16, vcc, 1.0, v8, 1.0
	v_mul_f32_e32 v17, v16, v15
	v_fma_f32 v18, -v14, v17, v16
	v_fmac_f32_e32 v17, v18, v15
	v_fma_f32 v14, -v14, v17, v16
	v_div_fmas_f32 v14, v14, v15, v17
	v_div_fixup_f32 v8, v14, v8, 1.0
	v_pk_mul_f32 v[4:5], v[8:9], v[4:5]
	v_pk_add_f32 v[8:9], v[10:11], 1.0 op_sel_hi:[1,0]
	v_pk_mul_f32 v[4:5], v[4:5], v[62:63]
	v_div_scale_f32 v10, s[46:47], v9, v9, 1.0
	v_rcp_f32_e32 v11, v10
	s_nop 0
	v_fma_f32 v14, -v10, v11, 1.0
	v_fmac_f32_e32 v11, v14, v11
	v_div_scale_f32 v14, vcc, 1.0, v9, 1.0
	v_mul_f32_e32 v15, v14, v11
	v_fma_f32 v16, -v10, v15, v14
	v_fmac_f32_e32 v15, v16, v11
	v_fma_f32 v10, -v10, v15, v14
	v_div_fmas_f32 v10, v10, v11, v15
	v_div_fixup_f32 v9, v10, v9, 1.0
	v_div_scale_f32 v10, s[46:47], v8, v8, 1.0
	v_rcp_f32_e32 v11, v10
	s_nop 0
	v_fma_f32 v14, -v10, v11, 1.0
	v_fmac_f32_e32 v11, v14, v11
	v_div_scale_f32 v14, vcc, 1.0, v8, 1.0
	v_mul_f32_e32 v15, v14, v11
	v_fma_f32 v16, -v10, v15, v14
	v_fmac_f32_e32 v15, v16, v11
	v_fma_f32 v10, -v10, v15, v14
	v_div_fmas_f32 v10, v10, v11, v15
	v_div_fixup_f32 v8, v10, v8, 1.0
	v_pk_mul_f32 v[6:7], v[8:9], v[6:7]
	s_nop 0
	v_pk_mul_f32 v[6:7], v[6:7], v[60:61]
	global_store_dwordx4 v[12:13], v[4:7], off
	ds_write_b128 v43, v[0:3]
	ds_write_b128 v43, v[4:7] offset:128
	v_add_u32_e32 v0, 0x300, v41
	v_ashrrev_i32_e32 v4, 4, v0
	v_ashrrev_i32_e32 v5, 31, v4
	v_lshl_or_b32 v41, v4, 9, v112
	v_lshlrev_b64 v[4:5], 10, v[4:5]
	v_lshl_add_u64 v[100:101], v[4:5], 0, s[54:55]
	v_lshl_add_u64 v[4:5], v[100:101], 1, v[48:49]
	ds_read_b128 v[12:15], v41
	ds_read_b128 v[0:3], v41 offset:128
	global_load_dwordx2 v[4:5], v[4:5], off
	s_waitcnt vmcnt(0)
	v_lshlrev_b32_e32 v62, 16, v4
	v_and_b32_e32 v63, 0xffff0000, v4
	v_lshlrev_b32_e32 v60, 16, v5
	v_and_b32_e32 v61, 0xffff0000, v5
	global_load_dwordx4 v[16:19], v[50:51], off
	global_load_dwordx4 v[8:11], v[52:53], off
	global_load_dwordx4 v[4:7], v[54:55], off
	s_waitcnt vmcnt(2) lgkmcnt(1)
	v_add_f32_e32 v12, v12, v16
	v_mul_f32_e32 v12, 0xbfb8aa3b, v12
	v_exp_f32_e32 v12, v12
	s_waitcnt vmcnt(1) lgkmcnt(0)
	v_add_f32_e32 v0, v0, v8
	v_mul_f32_e32 v0, 0xbfb8aa3b, v0
	v_exp_f32_e32 v8, v0
	v_add_f32_e32 v12, 1.0, v12
	v_div_scale_f32 v16, s[46:47], v12, v12, 1.0
	v_rcp_f32_e32 v43, v16
	s_waitcnt vmcnt(0)
	v_add_f32_e32 v1, v1, v9
	v_fma_f32 v45, -v16, v43, 1.0
	v_fmac_f32_e32 v43, v45, v43
	v_div_scale_f32 v45, vcc, 1.0, v12, 1.0
	v_mul_f32_e32 v47, v45, v43
	v_fma_f32 v113, -v16, v47, v45
	v_fmac_f32_e32 v47, v113, v43
	v_fma_f32 v16, -v16, v47, v45
	v_div_fmas_f32 v16, v16, v43, v47
	v_div_fixup_f32 v12, v16, v12, 1.0
	v_mul_f32_e32 v1, 0xbfb8aa3b, v1
	v_exp_f32_e32 v9, v1
	v_add_f32_e32 v2, v2, v10
	v_mul_f32_e32 v2, 0xbfb8aa3b, v2
	v_exp_f32_e32 v10, v2
	v_mov_b32_e32 v0, v240
	v_mul_f32_e32 v0, v12, v0
	v_mul_f32_e32 v0, 0x3fb8aa3b, v0
	v_exp_f32_e32 v0, v0
	v_add_f32_e32 v3, v3, v11
	v_fma_f32 v4, -v0, v0, 1.0
	v_max_f32_e32 v4, 0, v4
	v_cmp_gt_f32_e32 vcc, s69, v4
	v_mul_f32_e32 v12, 0x4f800000, v4
	s_nop 0
	v_cndmask_b32_e32 v4, v4, v12, vcc
	v_sqrt_f32_e32 v12, v4
	v_mul_f32_e32 v3, 0xbfb8aa3b, v3
	v_exp_f32_e32 v11, v3
	v_add_u32_e32 v16, -1, v12
	v_fma_f32 v43, -v16, v12, v4
	v_cmp_ge_f32_e64 s[46:47], 0, v43
	v_add_u32_e32 v43, 1, v12
	s_nop 0
	v_cndmask_b32_e64 v16, v12, v16, s[46:47]
	v_fma_f32 v12, -v43, v12, v4
	v_cmp_lt_f32_e64 s[46:47], 0, v12
	v_pk_add_f32 v[8:9], v[8:9], 1.0 op_sel_hi:[1,0]
	s_nop 0
	v_cndmask_b32_e64 v12, v16, v43, s[46:47]
	v_mul_f32_e32 v16, 0x37800000, v12
	v_cndmask_b32_e32 v12, v12, v16, vcc
	v_cmp_class_f32_e32 vcc, v4, v186
	s_nop 1
	v_cndmask_b32_e32 v4, v12, v4, vcc
	v_add_f32_e32 v12, v13, v17
	v_mul_f32_e32 v12, 0xbfb8aa3b, v12
	v_exp_f32_e32 v12, v12
	s_nop 0
	v_add_f32_e32 v12, 1.0, v12
	v_div_scale_f32 v13, s[46:47], v12, v12, 1.0
	v_rcp_f32_e32 v16, v13
	s_nop 0
	v_fma_f32 v17, -v13, v16, 1.0
	v_fmac_f32_e32 v16, v17, v16
	v_div_scale_f32 v17, vcc, 1.0, v12, 1.0
	v_mul_f32_e32 v43, v17, v16
	v_fma_f32 v45, -v13, v43, v17
	v_fmac_f32_e32 v43, v45, v16
	v_fma_f32 v13, -v13, v43, v17
	v_div_fmas_f32 v13, v13, v16, v43
	v_div_fixup_f32 v16, v13, v12, 1.0
	s_nop 1
	s_nop 1
	s_nop 1
	v_mov_b32_e32 v1, v241
	v_mul_f32_e32 v1, v16, v1
	v_mul_f32_e32 v1, 0x3fb8aa3b, v1
	v_exp_f32_e32 v1, v1
	s_nop 0
	v_fma_f32 v5, -v1, v1, 1.0
	v_max_f32_e32 v5, 0, v5
	v_cmp_gt_f32_e32 vcc, s69, v5
	v_mul_f32_e32 v12, 0x4f800000, v5
	s_nop 0
	v_cndmask_b32_e32 v5, v5, v12, vcc
	v_sqrt_f32_e32 v12, v5
	s_nop 0
	v_add_u32_e32 v13, -1, v12
	v_fma_f32 v16, -v13, v12, v5
	v_cmp_ge_f32_e64 s[46:47], 0, v16
	v_add_u32_e32 v16, 1, v12
	s_nop 0
	v_cndmask_b32_e64 v13, v12, v13, s[46:47]
	v_fma_f32 v12, -v16, v12, v5
	v_cmp_lt_f32_e64 s[46:47], 0, v12
	s_nop 1
; DEVI float sigmoidf_(float x) { return 1.f / (1.f + __expf(-x)); }
; DEVI void gate_tile(const Params& P, int l, int pm, int q, char* smem, int tid) {
;     ...
;   for (int q = 0; q < 8; ++q) {
;     const int id = tid + 256 * q, row = id >> 4, g4 = id & 15;
;     const int cl = g4 * 4, wcc = cl >> 5, c32 = cl & 31;
;     const long grow = (long)pm * 128 + row;
;     const int col = nb * 128 + hb * 64 + cl;
;     float4 rp = *reinterpret_cast<const float4*>(T + row * 128 + wcc * 64 + c32);
;     float4 gp = *reinterpret_cast<const float4*>(T + row * 128 + wcc * 64 + 32 + c32);
;     float xv[4], bav[4], bxv[4], lmv[4];
;     load4bf(cb + grow * 1024 + col, xv);
;     ld4f(ba + col, bav); ld4f(bx + col, bxv); ld4f(lam + col, lmv);
;     const float rpa[4] = {rp.x, rp.y, rp.z, rp.w}, gpa[4] = {gp.x, gp.y, gp.z, gp.w};
;     float av[4], uv[4];
; #pragma unroll
;     for (int i = 0; i < 4; ++i) {
;       float r = sigmoidf_(rpa[i] + bav[i]);
;       float gi = sigmoidf_(gpa[i] + bxv[i]);
;       float a = __expf(-8.f * log1pf(__expf(-lmv[i])) * r);
;       av[i] = a;
;       uv[i] = sqrtf(fmaxf(1.f - a * a, 0.f)) * gi * xv[i];
;     }
;     *reinterpret_cast<float4*>(au0 + grow * 1024 + col) = make_float4(av[0], av[1], av[2], av[3]);
;     *reinterpret_cast<float4*>(au1 + grow * 1024 + col) = make_float4(uv[0], uv[1], uv[2], uv[3]);
;     *reinterpret_cast<float4*>(Tw + row * 128 + wcc * 64 + c32) = make_float4(av[0], av[1], av[2], av[3]);
;     *reinterpret_cast<float4*>(Tw + row * 128 + wcc * 64 + 32 + c32) = make_float4(uv[0], uv[1], uv[2], uv[3]);
;   }
;   __syncthreads();
;   if (tid < 64) {
;     const int wcc = tid >> 5, c32 = tid & 31;
;     const float* ta = T + wcc * 64 + c32;
;     float Ap = 1.f, Hp = 0.f;
	v_cndmask_b32_e64 v12, v13, v16, s[46:47]
	v_mul_f32_e32 v13, 0x37800000, v12
	v_cndmask_b32_e32 v12, v12, v13, vcc
	v_cmp_class_f32_e32 vcc, v5, v186
	s_nop 1
	v_cndmask_b32_e32 v5, v12, v5, vcc
	v_add_f32_e32 v12, v14, v18
	v_mul_f32_e32 v12, 0xbfb8aa3b, v12
	v_exp_f32_e32 v12, v12
	s_nop 0
	v_add_f32_e32 v12, 1.0, v12
	v_div_scale_f32 v13, s[46:47], v12, v12, 1.0
	v_rcp_f32_e32 v14, v13
	s_nop 0
	v_fma_f32 v16, -v13, v14, 1.0
	v_fmac_f32_e32 v14, v16, v14
	v_div_scale_f32 v16, vcc, 1.0, v12, 1.0
	v_mul_f32_e32 v17, v16, v14
	v_fma_f32 v18, -v13, v17, v16
	v_fmac_f32_e32 v17, v18, v14
	v_fma_f32 v13, -v13, v17, v16
	v_div_fmas_f32 v13, v13, v14, v17
	v_div_fixup_f32 v14, v13, v12, 1.0
	s_nop 1
	s_nop 1
	s_nop 1
	v_mov_b32_e32 v2, v242
	v_mul_f32_e32 v2, v14, v2
	v_mul_f32_e32 v2, 0x3fb8aa3b, v2
	v_exp_f32_e32 v2, v2
	s_nop 0
	v_fma_f32 v6, -v2, v2, 1.0
	v_max_f32_e32 v6, 0, v6
	v_cmp_gt_f32_e32 vcc, s69, v6
	v_mul_f32_e32 v12, 0x4f800000, v6
	s_nop 0
	v_cndmask_b32_e32 v6, v6, v12, vcc
	v_sqrt_f32_e32 v12, v6
	s_nop 0
	v_add_u32_e32 v13, -1, v12
	v_fma_f32 v14, -v13, v12, v6
	v_cmp_ge_f32_e64 s[46:47], 0, v14
	v_add_u32_e32 v14, 1, v12
	s_nop 0
	v_cndmask_b32_e64 v13, v12, v13, s[46:47]
	v_fma_f32 v12, -v14, v12, v6
	v_cmp_lt_f32_e64 s[46:47], 0, v12
	s_nop 1
	v_cndmask_b32_e64 v12, v13, v14, s[46:47]
	v_mul_f32_e32 v13, 0x37800000, v12
	v_cndmask_b32_e32 v12, v12, v13, vcc
	v_cmp_class_f32_e32 vcc, v6, v186
	s_nop 1
	v_cndmask_b32_e32 v6, v12, v6, vcc
	v_add_f32_e32 v12, v15, v19
	v_mul_f32_e32 v12, 0xbfb8aa3b, v12
	v_exp_f32_e32 v12, v12
	s_nop 0
	v_add_f32_e32 v12, 1.0, v12
	v_div_scale_f32 v13, s[46:47], v12, v12, 1.0
	v_rcp_f32_e32 v14, v13
	s_nop 0
	v_fma_f32 v15, -v13, v14, 1.0
	v_fmac_f32_e32 v14, v15, v14
	v_div_scale_f32 v15, vcc, 1.0, v12, 1.0
	v_mul_f32_e32 v16, v15, v14
	v_fma_f32 v17, -v13, v16, v15
	v_fmac_f32_e32 v16, v17, v14
	v_fma_f32 v13, -v13, v16, v15
	v_div_fmas_f32 v13, v13, v14, v16
	v_div_fixup_f32 v14, v13, v12, 1.0
	s_nop 1
	s_nop 1
	s_nop 1
	v_mov_b32_e32 v3, v243
	v_mul_f32_e32 v3, v14, v3
	v_mul_f32_e32 v3, 0x3fb8aa3b, v3
	v_exp_f32_e32 v3, v3
	s_nop 0
	v_fma_f32 v7, -v3, v3, 1.0
	v_max_f32_e32 v7, 0, v7
	v_cmp_gt_f32_e32 vcc, s69, v7
	v_mul_f32_e32 v12, 0x4f800000, v7
	s_nop 0
	v_cndmask_b32_e32 v7, v7, v12, vcc
	v_sqrt_f32_e32 v12, v7
	s_nop 0
	v_add_u32_e32 v13, -1, v12
	v_fma_f32 v14, -v13, v12, v7
	v_cmp_ge_f32_e64 s[46:47], 0, v14
	v_add_u32_e32 v14, 1, v12
	s_nop 0
	v_cndmask_b32_e64 v13, v12, v13, s[46:47]
	v_fma_f32 v12, -v14, v12, v7
	v_cmp_lt_f32_e64 s[46:47], 0, v12
	s_nop 1
	v_cndmask_b32_e64 v12, v13, v14, s[46:47]
	v_mul_f32_e32 v13, 0x37800000, v12
	v_cndmask_b32_e32 v12, v12, v13, vcc
	v_cmp_class_f32_e32 vcc, v7, v186
	s_nop 1
	v_cndmask_b32_e32 v7, v12, v7, vcc
	v_lshlrev_b64 v[12:13], 2, v[100:101]
	v_lshl_add_u64 v[14:15], v[56:57], 0, v[12:13]
	global_store_dwordx4 v[14:15], v[0:3], off
	v_div_scale_f32 v14, s[46:47], v9, v9, 1.0
	v_rcp_f32_e32 v15, v14
	v_lshl_add_u64 v[12:13], v[58:59], 0, v[12:13]
	v_fma_f32 v16, -v14, v15, 1.0
	v_fmac_f32_e32 v15, v16, v15
	v_div_scale_f32 v16, vcc, 1.0, v9, 1.0
	v_mul_f32_e32 v17, v16, v15
	v_fma_f32 v18, -v14, v17, v16
	v_fmac_f32_e32 v17, v18, v15
	v_fma_f32 v14, -v14, v17, v16
	v_div_fmas_f32 v14, v14, v15, v17
	v_div_fixup_f32 v9, v14, v9, 1.0
	v_div_scale_f32 v14, s[46:47], v8, v8, 1.0
	v_rcp_f32_e32 v15, v14
	s_nop 0
	v_fma_f32 v16, -v14, v15, 1.0
	v_fmac_f32_e32 v15, v16, v15
	v_div_scale_f32 v16, vcc, 1.0, v8, 1.0
	v_mul_f32_e32 v17, v16, v15
	v_fma_f32 v18, -v14, v17, v16
	v_fmac_f32_e32 v17, v18, v15
	v_fma_f32 v14, -v14, v17, v16
	v_div_fmas_f32 v14, v14, v15, v17
	v_div_fixup_f32 v8, v14, v8, 1.0
	v_pk_mul_f32 v[4:5], v[8:9], v[4:5]
	v_pk_add_f32 v[8:9], v[10:11], 1.0 op_sel_hi:[1,0]
	v_pk_mul_f32 v[4:5], v[4:5], v[62:63]
	v_div_scale_f32 v10, s[46:47], v9, v9, 1.0
	v_rcp_f32_e32 v11, v10
	s_nop 0
	v_fma_f32 v14, -v10, v11, 1.0
	v_fmac_f32_e32 v11, v14, v11
	v_div_scale_f32 v14, vcc, 1.0, v9, 1.0
	v_mul_f32_e32 v15, v14, v11
	v_fma_f32 v16, -v10, v15, v14
	v_fmac_f32_e32 v15, v16, v11
	v_fma_f32 v10, -v10, v15, v14
	v_div_fmas_f32 v10, v10, v11, v15
	v_div_fixup_f32 v9, v10, v9, 1.0
	v_div_scale_f32 v10, s[46:47], v8, v8, 1.0
	v_rcp_f32_e32 v11, v10
	s_nop 0
	v_fma_f32 v14, -v10, v11, 1.0
	v_fmac_f32_e32 v11, v14, v11
	v_div_scale_f32 v14, vcc, 1.0, v8, 1.0
	v_mul_f32_e32 v15, v14, v11
	v_fma_f32 v16, -v10, v15, v14
	v_fmac_f32_e32 v15, v16, v11
	v_fma_f32 v10, -v10, v15, v14
	v_div_fmas_f32 v10, v10, v11, v15
	v_div_fixup_f32 v8, v10, v8, 1.0
	v_pk_mul_f32 v[6:7], v[8:9], v[6:7]
	s_nop 0
	v_pk_mul_f32 v[6:7], v[6:7], v[60:61]
	global_store_dwordx4 v[12:13], v[4:7], off
	ds_write_b128 v41, v[0:3]
	ds_write_b128 v41, v[4:7] offset:128
	s_cbranch_scc0 .LBB0_459
	s_waitcnt lgkmcnt(0)
	s_barrier
	s_and_saveexec_b64 s[46:47], s[44:45]
	s_cbranch_execz .LBB0_451
	v_mov_b32_e32 v1, 1.0
	v_mov_b32_e32 v2, 0
	s_mov_b32 s54, -16
	v_mov_b32_e32 v4, v111
